# GEMM K-loops: duplicate lgkmcnt(0) wait at the head of each MFMA cluster removed (the identical wait two instructions earlier remains)
# speedup vs baseline: 1.0182x; 1.0057x over previous
.LBB0_58:
	v_or_b32_e32 v142, 0x10000, v146
	v_add_u32_e32 v143, 0x10400, v146
	ds_read_b128 v[148:151], v142
	ds_read_b128 v[152:155], v143
	v_add_u32_e32 v142, 0x10800, v146
	v_add_u32_e32 v143, 0x10c00, v146
	ds_read_b128 v[156:159], v142
	ds_read_b128 v[160:163], v143
	s_add_u32 s10, s8, 0xfff50080
	s_addc_u32 s11, s9, -1
	s_cmp_eq_u32 s43, 40
	s_cselect_b32 s13, s5, s11
	s_cselect_b32 s12, s4, s10
	s_cselect_b32 s11, s7, s42
	s_cselect_b32 s10, s6, s41
	s_mov_b32 m0, s35
	v_lshl_add_u64 v[142:143], s[8:9], 0, v[138:139]
	ds_read_b128 v[164:167], v145
	ds_read_b128 v[168:171], v145 offset:1024
	ds_read_b128 v[172:175], v145 offset:2048
	ds_read_b128 v[176:179], v145 offset:3072
	ds_read_b128 v[194:197], v145 offset:4096
	ds_read_b128 v[198:201], v145 offset:5120
	ds_read_b128 v[202:205], v145 offset:6144
	ds_read_b128 v[206:209], v145 offset:7168
	global_load_lds_dwordx4 v[142:143], off
	v_lshl_add_u64 v[142:143], s[8:9], 0, v[140:141]
	s_mov_b32 m0, s36
	s_nop 0
	global_load_lds_dwordx4 v[142:143], off
	s_waitcnt lgkmcnt(8)
	s_barrier
	s_waitcnt lgkmcnt(0)
	s_setprio 1
	v_mfma_f32_16x16x32_bf16 v[128:131], v[148:151], v[164:167], v[128:131]
	v_mfma_f32_16x16x32_bf16 v[124:127], v[156:159], v[164:167], v[124:127]
	v_mfma_f32_16x16x32_bf16 v[120:123], v[148:151], v[172:175], v[120:123]
	v_mfma_f32_16x16x32_bf16 v[112:115], v[156:159], v[172:175], v[112:115]
	v_mfma_f32_16x16x32_bf16 v[104:107], v[148:151], v[194:197], v[104:107]
	v_mfma_f32_16x16x32_bf16 v[96:99], v[156:159], v[194:197], v[96:99]
	v_mfma_f32_16x16x32_bf16 v[84:87], v[148:151], v[202:205], v[84:87]
	v_mfma_f32_16x16x32_bf16 v[76:79], v[156:159], v[202:205], v[76:79]
	v_mfma_f32_16x16x32_bf16 v[128:131], v[152:155], v[168:171], v[128:131]
	v_mfma_f32_16x16x32_bf16 v[124:127], v[160:163], v[168:171], v[124:127]
	v_mfma_f32_16x16x32_bf16 v[120:123], v[152:155], v[176:179], v[120:123]
	v_mfma_f32_16x16x32_bf16 v[112:115], v[160:163], v[176:179], v[112:115]
	v_mfma_f32_16x16x32_bf16 v[104:107], v[152:155], v[198:201], v[104:107]
	v_mfma_f32_16x16x32_bf16 v[96:99], v[160:163], v[198:201], v[96:99]
	v_mfma_f32_16x16x32_bf16 v[84:87], v[152:155], v[206:209], v[84:87]
	v_mfma_f32_16x16x32_bf16 v[76:79], v[160:163], v[206:209], v[76:79]
	s_setprio 0
	s_barrier
	v_or_b32_e32 v142, 0x14000, v146
	v_add_u32_e32 v143, 0x14400, v146
	ds_read_b128 v[210:213], v142
	ds_read_b128 v[214:217], v143
	v_add_u32_e32 v142, 0x14800, v146
	v_add_u32_e32 v143, 0x14c00, v146
	s_mov_b32 m0, s17
	ds_read_b128 v[218:221], v142
	ds_read_b128 v[222:225], v143
	v_lshl_add_u64 v[142:143], s[10:11], 0, v[2:3]
	global_load_lds_dwordx4 v[142:143], off
	v_lshl_add_u64 v[240:241], s[10:11], 0, v[132:133]
	s_mov_b32 m0, s18
	s_nop 0
	global_load_lds_dwordx4 v[240:241], off
	s_barrier
	s_waitcnt lgkmcnt(0)
	s_setprio 1
	v_mfma_f32_16x16x32_bf16 v[116:119], v[210:213], v[164:167], v[116:119]
	v_mfma_f32_16x16x32_bf16 v[108:111], v[218:221], v[164:167], v[108:111]
	v_mfma_f32_16x16x32_bf16 v[100:103], v[210:213], v[172:175], v[100:103]
	v_mfma_f32_16x16x32_bf16 v[92:95], v[218:221], v[172:175], v[92:95]
	v_mfma_f32_16x16x32_bf16 v[88:91], v[210:213], v[194:197], v[88:91]
	v_mfma_f32_16x16x32_bf16 v[80:83], v[218:221], v[194:197], v[80:83]
	v_mfma_f32_16x16x32_bf16 v[72:75], v[210:213], v[202:205], v[72:75]
	v_mfma_f32_16x16x32_bf16 v[68:71], v[218:221], v[202:205], v[68:71]
	v_mfma_f32_16x16x32_bf16 v[116:119], v[214:217], v[168:171], v[116:119]
	v_mfma_f32_16x16x32_bf16 v[108:111], v[222:225], v[168:171], v[108:111]
	v_mfma_f32_16x16x32_bf16 v[100:103], v[214:217], v[176:179], v[100:103]
	v_mfma_f32_16x16x32_bf16 v[92:95], v[222:225], v[176:179], v[92:95]
	v_mfma_f32_16x16x32_bf16 v[88:91], v[214:217], v[198:201], v[88:91]
	v_mfma_f32_16x16x32_bf16 v[80:83], v[222:225], v[198:201], v[80:83]
	v_mfma_f32_16x16x32_bf16 v[72:75], v[214:217], v[206:209], v[72:75]
	v_mfma_f32_16x16x32_bf16 v[68:71], v[222:225], v[206:209], v[68:71]
	s_setprio 0
	s_mov_b32 m0, s16
	v_lshl_add_u64 v[242:243], s[12:13], 0, v[136:137]
	s_barrier
	ds_read_b128 v[164:167], v145 offset:16384
	ds_read_b128 v[168:171], v145 offset:17408
	ds_read_b128 v[172:175], v145 offset:18432
	ds_read_b128 v[176:179], v145 offset:19456
	ds_read_b128 v[194:197], v145 offset:20480
	ds_read_b128 v[198:201], v145 offset:21504
	ds_read_b128 v[202:205], v145 offset:22528
	ds_read_b128 v[206:209], v145 offset:23552
	global_load_lds_dwordx4 v[242:243], off
	v_lshl_add_u64 v[244:245], s[12:13], 0, v[134:135]
	s_mov_b32 m0, s19
	s_nop 0
	global_load_lds_dwordx4 v[244:245], off
	s_barrier
	s_waitcnt lgkmcnt(0)
	s_setprio 1
	v_mfma_f32_16x16x32_bf16 v[64:67], v[148:151], v[164:167], v[64:67]
	v_mfma_f32_16x16x32_bf16 v[60:63], v[156:159], v[164:167], v[60:63]
	v_mfma_f32_16x16x32_bf16 v[56:59], v[148:151], v[172:175], v[56:59]
	v_mfma_f32_16x16x32_bf16 v[48:51], v[156:159], v[172:175], v[48:51]
	v_mfma_f32_16x16x32_bf16 v[40:43], v[148:151], v[194:197], v[40:43]
	v_mfma_f32_16x16x32_bf16 v[32:35], v[156:159], v[194:197], v[32:35]
	v_mfma_f32_16x16x32_bf16 v[24:27], v[148:151], v[202:205], v[24:27]
	v_mfma_f32_16x16x32_bf16 v[16:19], v[156:159], v[202:205], v[16:19]
	v_mfma_f32_16x16x32_bf16 v[64:67], v[152:155], v[168:171], v[64:67]
	v_mfma_f32_16x16x32_bf16 v[60:63], v[160:163], v[168:171], v[60:63]
	v_mfma_f32_16x16x32_bf16 v[56:59], v[152:155], v[176:179], v[56:59]
	v_mfma_f32_16x16x32_bf16 v[48:51], v[160:163], v[176:179], v[48:51]
	v_mfma_f32_16x16x32_bf16 v[40:43], v[152:155], v[198:201], v[40:43]
	v_mfma_f32_16x16x32_bf16 v[32:35], v[160:163], v[198:201], v[32:35]
	v_mfma_f32_16x16x32_bf16 v[24:27], v[152:155], v[206:209], v[24:27]
	v_mfma_f32_16x16x32_bf16 v[16:19], v[160:163], v[206:209], v[16:19]
	s_setprio 0
	s_barrier
	s_add_u32 s44, s10, 0xb0000
	s_addc_u32 s45, s11, 0
	s_mov_b32 m0, s20
	v_lshl_add_u64 v[148:149], s[44:45], 0, v[2:3]
	global_load_lds_dwordx4 v[148:149], off
	v_lshl_add_u64 v[148:149], s[44:45], 0, v[132:133]
	s_mov_b32 m0, s21
	s_nop 0
	global_load_lds_dwordx4 v[148:149], off
	s_waitcnt vmcnt(6)
	s_barrier
	s_setprio 1
	v_mfma_f32_16x16x32_bf16 v[52:55], v[210:213], v[164:167], v[52:55]
	v_mfma_f32_16x16x32_bf16 v[44:47], v[218:221], v[164:167], v[44:47]
	v_mfma_f32_16x16x32_bf16 v[36:39], v[210:213], v[172:175], v[36:39]
	v_mfma_f32_16x16x32_bf16 v[28:31], v[218:221], v[172:175], v[28:31]
	v_mfma_f32_16x16x32_bf16 v[20:23], v[210:213], v[194:197], v[20:23]
	v_mfma_f32_16x16x32_bf16 v[12:15], v[218:221], v[194:197], v[12:15]
	v_mfma_f32_16x16x32_bf16 v[8:11], v[210:213], v[202:205], v[8:11]
	v_mfma_f32_16x16x32_bf16 v[4:7], v[218:221], v[202:205], v[4:7]
	v_mfma_f32_16x16x32_bf16 v[52:55], v[214:217], v[168:171], v[52:55]
	v_mfma_f32_16x16x32_bf16 v[44:47], v[222:225], v[168:171], v[44:47]
	v_mfma_f32_16x16x32_bf16 v[36:39], v[214:217], v[176:179], v[36:39]
	v_mfma_f32_16x16x32_bf16 v[28:31], v[222:225], v[176:179], v[28:31]
	v_mfma_f32_16x16x32_bf16 v[20:23], v[214:217], v[198:201], v[20:23]
	v_mfma_f32_16x16x32_bf16 v[12:15], v[222:225], v[198:201], v[12:15]
	v_mfma_f32_16x16x32_bf16 v[8:11], v[214:217], v[206:209], v[8:11]
	v_mfma_f32_16x16x32_bf16 v[4:7], v[222:225], v[206:209], v[4:7]
	s_setprio 0
	v_or_b32_e32 v148, 0x18000, v146
	v_add_u32_e32 v152, 0x18400, v146
	v_add_u32_e32 v156, 0x18800, v146
	v_add_u32_e32 v160, 0x18c00, v146
	s_barrier
	ds_read_b128 v[148:151], v148
	ds_read_b128 v[152:155], v152
	ds_read_b128 v[156:159], v156
	ds_read_b128 v[160:163], v160
	s_add_u32 s12, s12, 0xb0000
	s_addc_u32 s13, s13, 0
	s_mov_b32 m0, s22
	v_lshl_add_u64 v[210:211], s[12:13], 0, v[136:137]
	ds_read_b128 v[164:167], v145 offset:32768
	ds_read_b128 v[168:171], v145 offset:33792
	ds_read_b128 v[172:175], v145 offset:34816
	ds_read_b128 v[176:179], v145 offset:35840
	ds_read_b128 v[194:197], v145 offset:36864
	ds_read_b128 v[198:201], v145 offset:37888
	ds_read_b128 v[202:205], v145 offset:38912
	ds_read_b128 v[206:209], v145 offset:39936
	global_load_lds_dwordx4 v[210:211], off
	v_lshl_add_u64 v[210:211], s[12:13], 0, v[134:135]
	s_mov_b32 m0, s23
	s_nop 0
	global_load_lds_dwordx4 v[210:211], off
	s_waitcnt lgkmcnt(8)
	s_barrier
	s_waitcnt lgkmcnt(0)
	s_setprio 1
	v_mfma_f32_16x16x32_bf16 v[128:131], v[148:151], v[164:167], v[128:131]
	v_mfma_f32_16x16x32_bf16 v[124:127], v[156:159], v[164:167], v[124:127]
	v_mfma_f32_16x16x32_bf16 v[120:123], v[148:151], v[172:175], v[120:123]
	v_mfma_f32_16x16x32_bf16 v[112:115], v[156:159], v[172:175], v[112:115]
	v_mfma_f32_16x16x32_bf16 v[104:107], v[148:151], v[194:197], v[104:107]
	v_mfma_f32_16x16x32_bf16 v[96:99], v[156:159], v[194:197], v[96:99]
	v_mfma_f32_16x16x32_bf16 v[84:87], v[148:151], v[202:205], v[84:87]
	v_mfma_f32_16x16x32_bf16 v[76:79], v[156:159], v[202:205], v[76:79]
	v_mfma_f32_16x16x32_bf16 v[128:131], v[152:155], v[168:171], v[128:131]
	v_mfma_f32_16x16x32_bf16 v[124:127], v[160:163], v[168:171], v[124:127]
	v_mfma_f32_16x16x32_bf16 v[120:123], v[152:155], v[176:179], v[120:123]
	v_mfma_f32_16x16x32_bf16 v[112:115], v[160:163], v[176:179], v[112:115]
	v_mfma_f32_16x16x32_bf16 v[104:107], v[152:155], v[198:201], v[104:107]
	v_mfma_f32_16x16x32_bf16 v[96:99], v[160:163], v[198:201], v[96:99]
	v_mfma_f32_16x16x32_bf16 v[84:87], v[152:155], v[206:209], v[84:87]
	v_mfma_f32_16x16x32_bf16 v[76:79], v[160:163], v[206:209], v[76:79]
	s_setprio 0
	s_barrier
	v_or_b32_e32 v189, 0x1c000, v146
	v_add_u32_e32 v214, 0x1c400, v146
	s_mov_b32 m0, s25
	ds_read_b128 v[210:213], v189
	ds_read_b128 v[214:217], v214
	v_add_u32_e32 v189, 0x1c800, v146
	v_add_u32_e32 v222, 0x1cc00, v146
	v_lshl_add_u64 v[142:143], v[142:143], 0, s[82:83]
	ds_read_b128 v[218:221], v189
	ds_read_b128 v[222:225], v222
	global_load_lds_dwordx4 v[142:143], off
	v_lshl_add_u64 v[142:143], v[240:241], 0, s[82:83]
	s_mov_b32 m0, s26
	s_nop 0
	global_load_lds_dwordx4 v[142:143], off
	s_barrier
	s_waitcnt lgkmcnt(0)
	s_setprio 1
	v_mfma_f32_16x16x32_bf16 v[116:119], v[210:213], v[164:167], v[116:119]
	v_mfma_f32_16x16x32_bf16 v[108:111], v[218:221], v[164:167], v[108:111]
	v_mfma_f32_16x16x32_bf16 v[100:103], v[210:213], v[172:175], v[100:103]
	v_mfma_f32_16x16x32_bf16 v[92:95], v[218:221], v[172:175], v[92:95]
	v_mfma_f32_16x16x32_bf16 v[88:91], v[210:213], v[194:197], v[88:91]
	v_mfma_f32_16x16x32_bf16 v[80:83], v[218:221], v[194:197], v[80:83]
	v_mfma_f32_16x16x32_bf16 v[72:75], v[210:213], v[202:205], v[72:75]
	v_mfma_f32_16x16x32_bf16 v[68:71], v[218:221], v[202:205], v[68:71]
	v_mfma_f32_16x16x32_bf16 v[116:119], v[214:217], v[168:171], v[116:119]
	v_mfma_f32_16x16x32_bf16 v[108:111], v[222:225], v[168:171], v[108:111]
	v_mfma_f32_16x16x32_bf16 v[100:103], v[214:217], v[176:179], v[100:103]
	v_mfma_f32_16x16x32_bf16 v[92:95], v[222:225], v[176:179], v[92:95]
	v_mfma_f32_16x16x32_bf16 v[88:91], v[214:217], v[198:201], v[88:91]
	v_mfma_f32_16x16x32_bf16 v[80:83], v[222:225], v[198:201], v[80:83]
	v_mfma_f32_16x16x32_bf16 v[72:75], v[214:217], v[206:209], v[72:75]
	v_mfma_f32_16x16x32_bf16 v[68:71], v[222:225], v[206:209], v[68:71]
	s_setprio 0
	s_mov_b32 m0, s27
	v_lshl_add_u64 v[142:143], v[242:243], 0, s[82:83]
	s_barrier
	ds_read_b128 v[164:167], v145 offset:49152
	ds_read_b128 v[168:171], v145 offset:50176
	ds_read_b128 v[172:175], v145 offset:51200
	ds_read_b128 v[176:179], v145 offset:52224
	ds_read_b128 v[194:197], v145 offset:53248
	ds_read_b128 v[198:201], v145 offset:54272
	ds_read_b128 v[202:205], v145 offset:55296
	ds_read_b128 v[206:209], v145 offset:56320
	global_load_lds_dwordx4 v[142:143], off
	v_lshl_add_u64 v[142:143], v[244:245], 0, s[82:83]
	s_mov_b32 m0, s28
	s_nop 0
	global_load_lds_dwordx4 v[142:143], off
	s_barrier
	s_waitcnt lgkmcnt(0)
	s_setprio 1
	v_mfma_f32_16x16x32_bf16 v[64:67], v[148:151], v[164:167], v[64:67]
	v_mfma_f32_16x16x32_bf16 v[60:63], v[156:159], v[164:167], v[60:63]
	v_mfma_f32_16x16x32_bf16 v[56:59], v[148:151], v[172:175], v[56:59]
	v_mfma_f32_16x16x32_bf16 v[48:51], v[156:159], v[172:175], v[48:51]
	v_mfma_f32_16x16x32_bf16 v[40:43], v[148:151], v[194:197], v[40:43]
	v_mfma_f32_16x16x32_bf16 v[32:35], v[156:159], v[194:197], v[32:35]
	v_mfma_f32_16x16x32_bf16 v[24:27], v[148:151], v[202:205], v[24:27]
	v_mfma_f32_16x16x32_bf16 v[16:19], v[156:159], v[202:205], v[16:19]
	v_mfma_f32_16x16x32_bf16 v[64:67], v[152:155], v[168:171], v[64:67]
	v_mfma_f32_16x16x32_bf16 v[60:63], v[160:163], v[168:171], v[60:63]
	v_mfma_f32_16x16x32_bf16 v[56:59], v[152:155], v[176:179], v[56:59]
	v_mfma_f32_16x16x32_bf16 v[48:51], v[160:163], v[176:179], v[48:51]
	v_mfma_f32_16x16x32_bf16 v[40:43], v[152:155], v[198:201], v[40:43]
	v_mfma_f32_16x16x32_bf16 v[32:35], v[160:163], v[198:201], v[32:35]
	v_mfma_f32_16x16x32_bf16 v[24:27], v[152:155], v[206:209], v[24:27]
	v_mfma_f32_16x16x32_bf16 v[16:19], v[160:163], v[206:209], v[16:19]
	s_setprio 0
	s_barrier
	s_add_u32 s10, s10, 0xb0080
	s_addc_u32 s11, s11, 0
	s_mov_b32 m0, s29
	v_lshl_add_u64 v[142:143], s[10:11], 0, v[2:3]
	global_load_lds_dwordx4 v[142:143], off
	v_lshl_add_u64 v[142:143], s[10:11], 0, v[132:133]
	s_mov_b32 m0, s30
	s_nop 0
	global_load_lds_dwordx4 v[142:143], off
	s_waitcnt vmcnt(6)
	s_barrier
	s_setprio 1
	v_mfma_f32_16x16x32_bf16 v[52:55], v[210:213], v[164:167], v[52:55]
	v_mfma_f32_16x16x32_bf16 v[44:47], v[218:221], v[164:167], v[44:47]
	v_mfma_f32_16x16x32_bf16 v[36:39], v[210:213], v[172:175], v[36:39]
	v_mfma_f32_16x16x32_bf16 v[28:31], v[218:221], v[172:175], v[28:31]
	v_mfma_f32_16x16x32_bf16 v[20:23], v[210:213], v[194:197], v[20:23]
	v_mfma_f32_16x16x32_bf16 v[12:15], v[218:221], v[194:197], v[12:15]
	v_mfma_f32_16x16x32_bf16 v[8:11], v[210:213], v[202:205], v[8:11]
	v_mfma_f32_16x16x32_bf16 v[4:7], v[218:221], v[202:205], v[4:7]
	v_mfma_f32_16x16x32_bf16 v[52:55], v[214:217], v[168:171], v[52:55]
	v_mfma_f32_16x16x32_bf16 v[44:47], v[222:225], v[168:171], v[44:47]
	v_mfma_f32_16x16x32_bf16 v[36:39], v[214:217], v[176:179], v[36:39]
	v_mfma_f32_16x16x32_bf16 v[28:31], v[222:225], v[176:179], v[28:31]
	v_mfma_f32_16x16x32_bf16 v[20:23], v[214:217], v[198:201], v[20:23]
	v_mfma_f32_16x16x32_bf16 v[12:15], v[222:225], v[198:201], v[12:15]
	v_mfma_f32_16x16x32_bf16 v[8:11], v[214:217], v[206:209], v[8:11]
	v_mfma_f32_16x16x32_bf16 v[4:7], v[222:225], v[206:209], v[4:7]
	s_setprio 0
	s_add_i32 s43, s43, 2
	s_add_u32 s8, s8, 0x100
	s_addc_u32 s9, s9, 0
	s_add_u32 s41, s41, 0x100
	s_addc_u32 s42, s42, 0
	s_cmp_gt_u32 s43, 41
	s_barrier
	s_cbranch_scc0 .LBB0_58
	v_lshl_add_u32 v148, s40, 8, v144
	v_lshl_or_b32 v142, s39, 8, v147
	v_ashrrev_i32_e32 v149, 31, v148
	v_readlane_b32 s8, v253, 26
	v_ashrrev_i32_e32 v143, 31, v142
	v_lshlrev_b64 v[150:151], 11, v[148:149]
	v_readlane_b32 s9, v253, 27
	v_lshlrev_b64 v[152:153], 1, v[142:143]
	v_cvt_pk_bf16_f32 v128, v128, v129
	v_cvt_pk_bf16_f32 v129, v130, v131
	v_cvt_pk_bf16_f32 v130, v124, v125
	v_cvt_pk_bf16_f32 v131, v126, v127
	s_nop 0
	v_lshl_add_u64 v[150:151], s[8:9], 0, v[150:151]
	v_lshl_add_u64 v[142:143], v[150:151], 0, v[152:153]
	global_store_dwordx4 v[142:143], v[128:131], off sc1
	v_cvt_pk_bf16_f32 v116, v116, v117
	v_cvt_pk_bf16_f32 v117, v118, v119
	v_cvt_pk_bf16_f32 v118, v108, v109
	v_or_b32_e32 v108, 16, v148
	v_ashrrev_i32_e32 v109, 31, v108
	v_lshlrev_b64 v[108:109], 11, v[108:109]
	v_lshl_add_u64 v[108:109], s[8:9], 0, v[108:109]
	v_cvt_pk_bf16_f32 v119, v110, v111
	global_store_dwordx4 v[142:143], v[116:119], off offset:256 sc1
	s_mov_b32 s39, s37
	s_mov_b32 s40, s38
	v_lshl_add_u64 v[116:117], v[108:109], 0, v[152:153]
	v_cvt_pk_bf16_f32 v108, v120, v121
	v_cvt_pk_bf16_f32 v109, v122, v123
	v_cvt_pk_bf16_f32 v110, v112, v113
	v_cvt_pk_bf16_f32 v111, v114, v115
	global_store_dwordx4 v[116:117], v[108:111], off sc1
	v_cvt_pk_bf16_f32 v100, v100, v101
	v_cvt_pk_bf16_f32 v101, v102, v103
	v_cvt_pk_bf16_f32 v102, v92, v93
	v_or_b32_e32 v92, 32, v148
	v_ashrrev_i32_e32 v93, 31, v92
	v_lshlrev_b64 v[92:93], 11, v[92:93]
	v_lshl_add_u64 v[92:93], s[8:9], 0, v[92:93]
	v_cvt_pk_bf16_f32 v103, v94, v95
	global_store_dwordx4 v[116:117], v[100:103], off offset:256 sc1
	s_mov_b64 s[10:11], s[6:7]
	s_nop 0
	v_lshl_add_u64 v[100:101], v[92:93], 0, v[152:153]
	v_cvt_pk_bf16_f32 v92, v104, v105
	v_cvt_pk_bf16_f32 v93, v106, v107
	v_cvt_pk_bf16_f32 v94, v96, v97
	v_cvt_pk_bf16_f32 v95, v98, v99
	global_store_dwordx4 v[100:101], v[92:95], off sc1
	v_cvt_pk_bf16_f32 v88, v88, v89
	v_cvt_pk_bf16_f32 v89, v90, v91
	v_cvt_pk_bf16_f32 v90, v80, v81
	v_or_b32_e32 v80, 48, v148
	v_ashrrev_i32_e32 v81, 31, v80
	v_lshlrev_b64 v[80:81], 11, v[80:81]
	v_lshl_add_u64 v[80:81], s[8:9], 0, v[80:81]
	v_cvt_pk_bf16_f32 v91, v82, v83
	global_store_dwordx4 v[100:101], v[88:91], off offset:256 sc1
	s_mov_b64 s[8:9], 0x40000
	s_nop 0
	v_lshl_add_u64 v[88:89], v[80:81], 0, v[152:153]
	v_cvt_pk_bf16_f32 v80, v84, v85
	v_cvt_pk_bf16_f32 v81, v86, v87
	v_cvt_pk_bf16_f32 v82, v76, v77
	v_cvt_pk_bf16_f32 v83, v78, v79
	global_store_dwordx4 v[88:89], v[80:83], off sc1
	v_cvt_pk_bf16_f32 v72, v72, v73
	v_cvt_pk_bf16_f32 v73, v74, v75
	v_cvt_pk_bf16_f32 v74, v68, v69
	v_lshl_add_u64 v[68:69], v[142:143], 0, s[8:9]
	s_mov_b32 s8, 0x40000
	v_cvt_pk_bf16_f32 v75, v70, v71
	global_store_dwordx4 v[88:89], v[72:75], off offset:256 sc1
	v_cvt_pk_bf16_f32 v64, v64, v65
	v_cvt_pk_bf16_f32 v65, v66, v67
	v_cvt_pk_bf16_f32 v66, v60, v61
	v_add_co_u32_e32 v60, vcc, s8, v142
	v_cvt_pk_bf16_f32 v67, v62, v63
	s_mov_b64 s[8:9], 0x48000
	s_nop 0
	v_addc_co_u32_e32 v61, vcc, 0, v143, vcc
	global_store_dwordx4 v[60:61], v[64:67], off sc1
	v_cvt_pk_bf16_f32 v52, v52, v53
	v_cvt_pk_bf16_f32 v53, v54, v55
	v_cvt_pk_bf16_f32 v54, v44, v45
	v_cvt_pk_bf16_f32 v55, v46, v47
	global_store_dwordx4 v[68:69], v[52:55], off offset:256 sc1
	v_cvt_pk_bf16_f32 v44, v56, v57
	v_cvt_pk_bf16_f32 v45, v58, v59
	v_cvt_pk_bf16_f32 v46, v48, v49
	v_cvt_pk_bf16_f32 v47, v50, v51
	s_nop 1
	v_lshl_add_u64 v[52:53], v[142:143], 0, s[8:9]
	s_mov_b32 s8, 0x48000
	v_add_co_u32_e32 v48, vcc, s8, v142
	s_mov_b64 s[8:9], 0x50000
	s_nop 0
	v_addc_co_u32_e32 v49, vcc, 0, v143, vcc
	global_store_dwordx4 v[48:49], v[44:47], off sc1
	v_cvt_pk_bf16_f32 v36, v36, v37
	v_cvt_pk_bf16_f32 v37, v38, v39
	v_cvt_pk_bf16_f32 v38, v28, v29
	v_cvt_pk_bf16_f32 v39, v30, v31
	global_store_dwordx4 v[52:53], v[36:39], off offset:256 sc1
	v_cvt_pk_bf16_f32 v28, v40, v41
	v_cvt_pk_bf16_f32 v29, v42, v43
	v_cvt_pk_bf16_f32 v30, v32, v33
	v_cvt_pk_bf16_f32 v31, v34, v35
	s_nop 1
	v_lshl_add_u64 v[36:37], v[142:143], 0, s[8:9]
	s_mov_b32 s8, 0x50000
	v_add_co_u32_e32 v32, vcc, s8, v142
	s_mov_b64 s[8:9], 0x58000
	s_nop 0
	v_addc_co_u32_e32 v33, vcc, 0, v143, vcc
	global_store_dwordx4 v[32:33], v[28:31], off sc1
	v_cvt_pk_bf16_f32 v20, v20, v21
	v_cvt_pk_bf16_f32 v21, v22, v23
	v_cvt_pk_bf16_f32 v22, v12, v13
	v_cvt_pk_bf16_f32 v23, v14, v15
	global_store_dwordx4 v[36:37], v[20:23], off offset:256 sc1
	v_cvt_pk_bf16_f32 v12, v24, v25
	v_cvt_pk_bf16_f32 v13, v26, v27
	v_cvt_pk_bf16_f32 v14, v16, v17
	v_cvt_pk_bf16_f32 v15, v18, v19
	s_nop 1
	v_lshl_add_u64 v[20:21], v[142:143], 0, s[8:9]
	s_mov_b32 s8, 0x58000
	v_add_co_u32_e32 v16, vcc, s8, v142
	s_mov_b64 s[8:9], s[4:5]
	s_nop 0
	v_addc_co_u32_e32 v17, vcc, 0, v143, vcc
	s_and_b64 vcc, exec, s[2:3]
	global_store_dwordx4 v[16:17], v[12:15], off sc1
	v_cvt_pk_bf16_f32 v8, v8, v9
	v_cvt_pk_bf16_f32 v9, v10, v11
	v_cvt_pk_bf16_f32 v10, v4, v5
	v_cvt_pk_bf16_f32 v11, v6, v7
	global_store_dwordx4 v[20:21], v[8:11], off offset:256 sc1
	s_cbranch_vccz .LBB0_47
	s_waitcnt vmcnt(0)
	s_cmpk_gt_u32 s0, 0xff
	v_readlane_b32 s34, v251, 48
	s_cbranch_scc1 .LBB0_62
	s_barrier

.LBB0_95:
	v_or_b32_e32 v2, 0x10000, v241
	v_add_u32_e32 v120, 0x10400, v241
	ds_read_b128 v[116:119], v2
	ds_read_b128 v[120:123], v120
	v_add_u32_e32 v2, 0x10800, v241
	v_add_u32_e32 v128, 0x10c00, v241
	ds_read_b128 v[124:127], v2
	ds_read_b128 v[128:131], v128
	s_add_u32 s6, s4, 0xfffc0080
	s_addc_u32 s7, s5, -1
	s_cmp_eq_u32 s17, 12
	s_cselect_b32 s9, s10, s7
	s_cselect_b32 s8, s11, s6
	s_cselect_b32 s7, s12, s16
	s_cselect_b32 s6, s13, s15
	v_lshl_add_u64 v[206:207], s[4:5], 0, v[202:203]
	s_add_i32 m0, s96, 0xc000
	ds_read_b128 v[132:135], v240
	ds_read_b128 v[136:139], v240 offset:1024
	ds_read_b128 v[140:143], v240 offset:2048
	ds_read_b128 v[144:147], v240 offset:3072
	ds_read_b128 v[164:167], v240 offset:4096
	ds_read_b128 v[168:171], v240 offset:5120
	ds_read_b128 v[172:175], v240 offset:6144
	ds_read_b128 v[176:179], v240 offset:7168
	global_load_lds_dwordx4 v[206:207], off
	v_lshl_add_u64 v[206:207], s[4:5], 0, v[204:205]
	s_add_i32 m0, s96, 0xe000
	s_nop 0
	global_load_lds_dwordx4 v[206:207], off
	s_waitcnt lgkmcnt(8)
	s_barrier
	s_waitcnt lgkmcnt(0)
	s_setprio 1
	v_mfma_f32_16x16x32_bf16 v[160:163], v[116:119], v[132:135], v[160:163]
	v_mfma_f32_16x16x32_bf16 v[64:67], v[124:127], v[132:135], v[64:67]
	v_mfma_f32_16x16x32_bf16 v[152:155], v[116:119], v[140:143], v[152:155]
	v_mfma_f32_16x16x32_bf16 v[56:59], v[124:127], v[140:143], v[56:59]
	v_mfma_f32_16x16x32_bf16 v[112:115], v[116:119], v[164:167], v[112:115]
	v_mfma_f32_16x16x32_bf16 v[48:51], v[124:127], v[164:167], v[48:51]
	v_mfma_f32_16x16x32_bf16 v[100:103], v[116:119], v[172:175], v[100:103]
	v_mfma_f32_16x16x32_bf16 v[36:39], v[124:127], v[172:175], v[36:39]
	v_mfma_f32_16x16x32_bf16 v[160:163], v[120:123], v[136:139], v[160:163]
	v_mfma_f32_16x16x32_bf16 v[64:67], v[128:131], v[136:139], v[64:67]
	v_mfma_f32_16x16x32_bf16 v[152:155], v[120:123], v[144:147], v[152:155]
	v_mfma_f32_16x16x32_bf16 v[56:59], v[128:131], v[144:147], v[56:59]
	v_mfma_f32_16x16x32_bf16 v[112:115], v[120:123], v[168:171], v[112:115]
	v_mfma_f32_16x16x32_bf16 v[48:51], v[128:131], v[168:171], v[48:51]
	v_mfma_f32_16x16x32_bf16 v[100:103], v[120:123], v[176:179], v[100:103]
	v_mfma_f32_16x16x32_bf16 v[36:39], v[128:131], v[176:179], v[36:39]
	s_setprio 0
	s_barrier
	v_or_b32_e32 v2, 0x14000, v241
	v_add_u32_e32 v210, 0x14400, v241
	s_mov_b32 m0, s97
	ds_read_b128 v[206:209], v2
	ds_read_b128 v[210:213], v210
	v_add_u32_e32 v2, 0x14800, v241
	v_add_u32_e32 v218, 0x14c00, v241
	v_lshl_add_u64 v[242:243], s[6:7], 0, v[198:199]
	ds_read_b128 v[214:217], v2
	ds_read_b128 v[218:221], v218
	global_load_lds_dwordx4 v[242:243], off
	v_lshl_add_u64 v[244:245], s[6:7], 0, v[194:195]
	s_mov_b32 m0, s0
	s_nop 0
	global_load_lds_dwordx4 v[244:245], off
	s_barrier
	s_waitcnt lgkmcnt(0)
	s_setprio 1
	v_mfma_f32_16x16x32_bf16 v[156:159], v[206:209], v[132:135], v[156:159]
	v_mfma_f32_16x16x32_bf16 v[60:63], v[214:217], v[132:135], v[60:63]
	v_mfma_f32_16x16x32_bf16 v[52:55], v[214:217], v[140:143], v[52:55]
	v_mfma_f32_16x16x32_bf16 v[108:111], v[206:209], v[164:167], v[108:111]
	v_mfma_f32_16x16x32_bf16 v[44:47], v[214:217], v[164:167], v[44:47]
	v_mfma_f32_16x16x32_bf16 v[104:107], v[206:209], v[172:175], v[104:107]
	v_mfma_f32_16x16x32_bf16 v[40:43], v[214:217], v[172:175], v[40:43]
	v_mfma_f32_16x16x32_bf16 v[156:159], v[210:213], v[136:139], v[156:159]
	v_mfma_f32_16x16x32_bf16 v[60:63], v[218:221], v[136:139], v[60:63]
	v_mfma_f32_16x16x32_bf16 v[132:135], v[206:209], v[140:143], v[148:151]
	v_mfma_f32_16x16x32_bf16 v[52:55], v[218:221], v[144:147], v[52:55]
	v_mfma_f32_16x16x32_bf16 v[108:111], v[210:213], v[168:171], v[108:111]
	v_mfma_f32_16x16x32_bf16 v[44:47], v[218:221], v[168:171], v[44:47]
	v_mfma_f32_16x16x32_bf16 v[104:107], v[210:213], v[176:179], v[104:107]
	v_mfma_f32_16x16x32_bf16 v[40:43], v[218:221], v[176:179], v[40:43]
	v_mfma_f32_16x16x32_bf16 v[132:135], v[210:213], v[144:147], v[132:135]
	s_setprio 0
	s_mov_b32 m0, s96
	v_lshl_add_u64 v[246:247], s[8:9], 0, v[200:201]
	s_barrier
	ds_read_b128 v[136:139], v240 offset:16384
	ds_read_b128 v[140:143], v240 offset:17408
	ds_read_b128 v[144:147], v240 offset:18432
	ds_read_b128 v[148:151], v240 offset:19456
	ds_read_b128 v[164:167], v240 offset:20480
	ds_read_b128 v[168:171], v240 offset:21504
	ds_read_b128 v[172:175], v240 offset:22528
	ds_read_b128 v[176:179], v240 offset:23552
	global_load_lds_dwordx4 v[246:247], off
	v_lshl_add_u64 v[248:249], s[8:9], 0, v[196:197]
	s_mov_b32 m0, s48
	s_nop 0
	global_load_lds_dwordx4 v[248:249], off
	s_barrier
	s_waitcnt lgkmcnt(0)
	s_setprio 1
	v_mfma_f32_16x16x32_bf16 v[96:99], v[116:119], v[136:139], v[96:99]
	v_mfma_f32_16x16x32_bf16 v[32:35], v[124:127], v[136:139], v[32:35]
	v_mfma_f32_16x16x32_bf16 v[88:91], v[116:119], v[144:147], v[88:91]
	v_mfma_f32_16x16x32_bf16 v[24:27], v[124:127], v[144:147], v[24:27]
	v_mfma_f32_16x16x32_bf16 v[80:83], v[116:119], v[164:167], v[80:83]
	v_mfma_f32_16x16x32_bf16 v[16:19], v[124:127], v[164:167], v[16:19]
	v_mfma_f32_16x16x32_bf16 v[68:71], v[116:119], v[172:175], v[68:71]
	v_mfma_f32_16x16x32_bf16 v[4:7], v[124:127], v[172:175], v[4:7]
	v_mfma_f32_16x16x32_bf16 v[96:99], v[120:123], v[140:143], v[96:99]
	v_mfma_f32_16x16x32_bf16 v[32:35], v[128:131], v[140:143], v[32:35]
	v_mfma_f32_16x16x32_bf16 v[88:91], v[120:123], v[148:151], v[88:91]
	v_mfma_f32_16x16x32_bf16 v[24:27], v[128:131], v[148:151], v[24:27]
	v_mfma_f32_16x16x32_bf16 v[80:83], v[120:123], v[168:171], v[80:83]
	v_mfma_f32_16x16x32_bf16 v[16:19], v[128:131], v[168:171], v[16:19]
	v_mfma_f32_16x16x32_bf16 v[68:71], v[120:123], v[176:179], v[68:71]
	v_mfma_f32_16x16x32_bf16 v[4:7], v[128:131], v[176:179], v[4:7]
	s_setprio 0
	s_barrier
	s_add_u32 s20, s6, 0x40000
	s_addc_u32 s21, s7, 0
	s_mov_b32 m0, s58
	v_lshl_add_u64 v[116:117], s[20:21], 0, v[198:199]
	global_load_lds_dwordx4 v[116:117], off
	v_lshl_add_u64 v[116:117], s[20:21], 0, v[194:195]
	s_mov_b32 m0, s59
	s_nop 0
	global_load_lds_dwordx4 v[116:117], off
	s_waitcnt vmcnt(6)
	s_barrier
	s_setprio 1
	v_mfma_f32_16x16x32_bf16 v[92:95], v[206:209], v[136:139], v[92:95]
	v_mfma_f32_16x16x32_bf16 v[28:31], v[214:217], v[136:139], v[28:31]
	v_mfma_f32_16x16x32_bf16 v[84:87], v[206:209], v[144:147], v[84:87]
	v_mfma_f32_16x16x32_bf16 v[20:23], v[214:217], v[144:147], v[20:23]
	v_mfma_f32_16x16x32_bf16 v[76:79], v[206:209], v[164:167], v[76:79]
	v_mfma_f32_16x16x32_bf16 v[12:15], v[214:217], v[164:167], v[12:15]
	v_mfma_f32_16x16x32_bf16 v[72:75], v[206:209], v[172:175], v[72:75]
	v_mfma_f32_16x16x32_bf16 v[8:11], v[214:217], v[172:175], v[8:11]
	v_mfma_f32_16x16x32_bf16 v[92:95], v[210:213], v[140:143], v[92:95]
	v_mfma_f32_16x16x32_bf16 v[28:31], v[218:221], v[140:143], v[28:31]
	v_mfma_f32_16x16x32_bf16 v[84:87], v[210:213], v[148:151], v[84:87]
	v_mfma_f32_16x16x32_bf16 v[20:23], v[218:221], v[148:151], v[20:23]
	v_mfma_f32_16x16x32_bf16 v[76:79], v[210:213], v[168:171], v[76:79]
	v_mfma_f32_16x16x32_bf16 v[12:15], v[218:221], v[168:171], v[12:15]
	v_mfma_f32_16x16x32_bf16 v[72:75], v[210:213], v[176:179], v[72:75]
	v_mfma_f32_16x16x32_bf16 v[8:11], v[218:221], v[176:179], v[8:11]
	s_setprio 0
	v_or_b32_e32 v2, 0x18000, v241
	v_add_u32_e32 v120, 0x18400, v241
	s_barrier
	ds_read_b128 v[116:119], v2
	ds_read_b128 v[120:123], v120
	v_add_u32_e32 v2, 0x18800, v241
	v_add_u32_e32 v128, 0x18c00, v241
	ds_read_b128 v[124:127], v2
	ds_read_b128 v[128:131], v128
	s_add_u32 s8, s8, 0x40000
	s_addc_u32 s9, s9, 0
	s_mov_b32 m0, s52
	v_lshl_add_u64 v[148:149], s[8:9], 0, v[200:201]
	ds_read_b128 v[136:139], v240 offset:32768
	ds_read_b128 v[140:143], v240 offset:33792
	ds_read_b128 v[144:147], v240 offset:34816
	ds_read_b128 v[164:167], v240 offset:35840
	ds_read_b128 v[168:171], v240 offset:36864
	ds_read_b128 v[172:175], v240 offset:37888
	ds_read_b128 v[176:179], v240 offset:38912
	ds_read_b128 v[206:209], v240 offset:39936
	global_load_lds_dwordx4 v[148:149], off
	v_lshl_add_u64 v[148:149], s[8:9], 0, v[196:197]
	s_mov_b32 m0, s53
	s_nop 0
	global_load_lds_dwordx4 v[148:149], off
	s_waitcnt lgkmcnt(8)
	s_barrier
	s_waitcnt lgkmcnt(0)
	s_setprio 1
	v_mfma_f32_16x16x32_bf16 v[148:151], v[116:119], v[136:139], v[160:163]
	v_mfma_f32_16x16x32_bf16 v[160:163], v[120:123], v[140:143], v[148:151]
	v_mfma_f32_16x16x32_bf16 v[64:67], v[124:127], v[136:139], v[64:67]
	v_mfma_f32_16x16x32_bf16 v[148:151], v[116:119], v[144:147], v[152:155]
	v_mfma_f32_16x16x32_bf16 v[56:59], v[124:127], v[144:147], v[56:59]
	v_mfma_f32_16x16x32_bf16 v[112:115], v[116:119], v[168:171], v[112:115]
	v_mfma_f32_16x16x32_bf16 v[48:51], v[124:127], v[168:171], v[48:51]
	v_mfma_f32_16x16x32_bf16 v[100:103], v[116:119], v[176:179], v[100:103]
	v_mfma_f32_16x16x32_bf16 v[36:39], v[124:127], v[176:179], v[36:39]
	v_mfma_f32_16x16x32_bf16 v[64:67], v[128:131], v[140:143], v[64:67]
	v_mfma_f32_16x16x32_bf16 v[152:155], v[120:123], v[164:167], v[148:151]
	v_mfma_f32_16x16x32_bf16 v[56:59], v[128:131], v[164:167], v[56:59]
	v_mfma_f32_16x16x32_bf16 v[112:115], v[120:123], v[172:175], v[112:115]
	v_mfma_f32_16x16x32_bf16 v[48:51], v[128:131], v[172:175], v[48:51]
	v_mfma_f32_16x16x32_bf16 v[100:103], v[120:123], v[206:209], v[100:103]
	v_mfma_f32_16x16x32_bf16 v[36:39], v[128:131], v[206:209], v[36:39]
	s_setprio 0
	s_barrier
	v_or_b32_e32 v2, 0x1c000, v241
	v_add_u32_e32 v148, 0x1c400, v241
	ds_read_b128 v[210:213], v2
	ds_read_b128 v[214:217], v148
	v_add_u32_e32 v2, 0x1c800, v241
	v_add_u32_e32 v148, 0x1cc00, v241
	s_mov_b32 m0, s50
	ds_read_b128 v[218:221], v2
	ds_read_b128 v[222:225], v148
	v_lshl_add_u64 v[148:149], v[242:243], 0, s[82:83]
	global_load_lds_dwordx4 v[148:149], off
	v_lshl_add_u64 v[148:149], v[244:245], 0, s[82:83]
	s_mov_b32 m0, s51
	s_nop 0
	global_load_lds_dwordx4 v[148:149], off
	s_barrier
	s_waitcnt lgkmcnt(0)
	s_setprio 1
	v_mfma_f32_16x16x32_bf16 v[148:151], v[210:213], v[136:139], v[156:159]
	v_mfma_f32_16x16x32_bf16 v[60:63], v[218:221], v[136:139], v[60:63]
	v_mfma_f32_16x16x32_bf16 v[132:135], v[210:213], v[144:147], v[132:135]
	v_mfma_f32_16x16x32_bf16 v[52:55], v[218:221], v[144:147], v[52:55]
	v_mfma_f32_16x16x32_bf16 v[108:111], v[210:213], v[168:171], v[108:111]
	v_mfma_f32_16x16x32_bf16 v[44:47], v[218:221], v[168:171], v[44:47]
	v_mfma_f32_16x16x32_bf16 v[104:107], v[210:213], v[176:179], v[104:107]
	v_mfma_f32_16x16x32_bf16 v[40:43], v[218:221], v[176:179], v[40:43]
	v_mfma_f32_16x16x32_bf16 v[156:159], v[214:217], v[140:143], v[148:151]
	v_mfma_f32_16x16x32_bf16 v[60:63], v[222:225], v[140:143], v[60:63]
	v_mfma_f32_16x16x32_bf16 v[148:151], v[214:217], v[164:167], v[132:135]
	v_mfma_f32_16x16x32_bf16 v[52:55], v[222:225], v[164:167], v[52:55]
	v_mfma_f32_16x16x32_bf16 v[108:111], v[214:217], v[172:175], v[108:111]
	v_mfma_f32_16x16x32_bf16 v[44:47], v[222:225], v[172:175], v[44:47]
	v_mfma_f32_16x16x32_bf16 v[104:107], v[214:217], v[206:209], v[104:107]
	v_mfma_f32_16x16x32_bf16 v[40:43], v[222:225], v[206:209], v[40:43]
	s_setprio 0
	s_mov_b32 m0, s54
	v_lshl_add_u64 v[206:207], v[246:247], 0, s[82:83]
	s_barrier
	ds_read_b128 v[132:135], v240 offset:49152
	ds_read_b128 v[136:139], v240 offset:50176
	ds_read_b128 v[140:143], v240 offset:51200
	ds_read_b128 v[144:147], v240 offset:52224
	ds_read_b128 v[164:167], v240 offset:53248
	ds_read_b128 v[168:171], v240 offset:54272
	ds_read_b128 v[172:175], v240 offset:55296
	ds_read_b128 v[176:179], v240 offset:56320
	global_load_lds_dwordx4 v[206:207], off
	v_lshl_add_u64 v[206:207], v[248:249], 0, s[82:83]
	s_mov_b32 m0, s55
	s_nop 0
	global_load_lds_dwordx4 v[206:207], off
	s_barrier
	s_waitcnt lgkmcnt(0)
	s_setprio 1
	v_mfma_f32_16x16x32_bf16 v[96:99], v[116:119], v[132:135], v[96:99]
	v_mfma_f32_16x16x32_bf16 v[32:35], v[124:127], v[132:135], v[32:35]
	v_mfma_f32_16x16x32_bf16 v[88:91], v[116:119], v[140:143], v[88:91]
	v_mfma_f32_16x16x32_bf16 v[24:27], v[124:127], v[140:143], v[24:27]
	v_mfma_f32_16x16x32_bf16 v[80:83], v[116:119], v[164:167], v[80:83]
	v_mfma_f32_16x16x32_bf16 v[16:19], v[124:127], v[164:167], v[16:19]
	v_mfma_f32_16x16x32_bf16 v[68:71], v[116:119], v[172:175], v[68:71]
	v_mfma_f32_16x16x32_bf16 v[4:7], v[124:127], v[172:175], v[4:7]
	v_mfma_f32_16x16x32_bf16 v[96:99], v[120:123], v[136:139], v[96:99]
	v_mfma_f32_16x16x32_bf16 v[32:35], v[128:131], v[136:139], v[32:35]
	v_mfma_f32_16x16x32_bf16 v[88:91], v[120:123], v[144:147], v[88:91]
	v_mfma_f32_16x16x32_bf16 v[24:27], v[128:131], v[144:147], v[24:27]
	v_mfma_f32_16x16x32_bf16 v[80:83], v[120:123], v[168:171], v[80:83]
	v_mfma_f32_16x16x32_bf16 v[16:19], v[128:131], v[168:171], v[16:19]
	v_mfma_f32_16x16x32_bf16 v[68:71], v[120:123], v[176:179], v[68:71]
	v_mfma_f32_16x16x32_bf16 v[4:7], v[128:131], v[176:179], v[4:7]
	s_setprio 0
	s_barrier
	s_add_u32 s6, s6, 0x40080
	s_addc_u32 s7, s7, 0
	s_mov_b32 m0, s56
	v_lshl_add_u64 v[116:117], s[6:7], 0, v[198:199]
	global_load_lds_dwordx4 v[116:117], off
	v_lshl_add_u64 v[116:117], s[6:7], 0, v[194:195]
	s_mov_b32 m0, s57
	s_nop 0
	global_load_lds_dwordx4 v[116:117], off
	s_waitcnt vmcnt(6)
	s_barrier
	s_setprio 1
	v_mfma_f32_16x16x32_bf16 v[92:95], v[210:213], v[132:135], v[92:95]
	v_mfma_f32_16x16x32_bf16 v[28:31], v[218:221], v[132:135], v[28:31]
	v_mfma_f32_16x16x32_bf16 v[84:87], v[210:213], v[140:143], v[84:87]
	v_mfma_f32_16x16x32_bf16 v[20:23], v[218:221], v[140:143], v[20:23]
	v_mfma_f32_16x16x32_bf16 v[76:79], v[210:213], v[164:167], v[76:79]
	v_mfma_f32_16x16x32_bf16 v[12:15], v[218:221], v[164:167], v[12:15]
	v_mfma_f32_16x16x32_bf16 v[72:75], v[210:213], v[172:175], v[72:75]
	v_mfma_f32_16x16x32_bf16 v[8:11], v[218:221], v[172:175], v[8:11]
	v_mfma_f32_16x16x32_bf16 v[92:95], v[214:217], v[136:139], v[92:95]
	v_mfma_f32_16x16x32_bf16 v[28:31], v[222:225], v[136:139], v[28:31]
	v_mfma_f32_16x16x32_bf16 v[84:87], v[214:217], v[144:147], v[84:87]
	v_mfma_f32_16x16x32_bf16 v[20:23], v[222:225], v[144:147], v[20:23]
	v_mfma_f32_16x16x32_bf16 v[76:79], v[214:217], v[168:171], v[76:79]
	v_mfma_f32_16x16x32_bf16 v[12:15], v[222:225], v[168:171], v[12:15]
	v_mfma_f32_16x16x32_bf16 v[72:75], v[214:217], v[176:179], v[72:75]
	v_mfma_f32_16x16x32_bf16 v[8:11], v[222:225], v[176:179], v[8:11]
	s_setprio 0
	s_add_i32 s17, s17, 2
	s_add_u32 s4, s4, 0x100
	s_addc_u32 s5, s5, 0
	s_add_u32 s15, s15, 0x100
	s_addc_u32 s16, s16, 0
	s_cmp_gt_u32 s17, 13
	s_barrier
	s_cbranch_scc0 .LBB0_95

.LBB0_292:
	v_or_b32_e32 v142, 0x10000, v146
	v_add_u32_e32 v143, 0x10400, v146
	ds_read_b128 v[148:151], v142
	ds_read_b128 v[152:155], v143
	v_add_u32_e32 v142, 0x10800, v146
	v_add_u32_e32 v143, 0x10c00, v146
	ds_read_b128 v[156:159], v142
	ds_read_b128 v[160:163], v143
	s_add_u32 s14, s12, 0xfffc0080
	s_addc_u32 s15, s13, -1
	s_cmp_eq_u32 s45, 12
	s_cselect_b32 s17, s7, s15
	s_cselect_b32 s16, s41, s14
	s_cselect_b32 s15, s5, s44
	s_cselect_b32 s14, s42, s43
	v_lshl_add_u64 v[142:143], s[12:13], 0, v[138:139]
	s_add_i32 m0, s20, 0xc000
	ds_read_b128 v[164:167], v145
	ds_read_b128 v[168:171], v145 offset:1024
	ds_read_b128 v[172:175], v145 offset:2048
	ds_read_b128 v[176:179], v145 offset:3072
	ds_read_b128 v[194:197], v145 offset:4096
	ds_read_b128 v[198:201], v145 offset:5120
	ds_read_b128 v[202:205], v145 offset:6144
	ds_read_b128 v[206:209], v145 offset:7168
	global_load_lds_dwordx4 v[142:143], off
	v_lshl_add_u64 v[142:143], s[12:13], 0, v[140:141]
	s_add_i32 m0, s20, 0xe000
	s_nop 0
	global_load_lds_dwordx4 v[142:143], off
	s_waitcnt lgkmcnt(8)
	s_barrier
	s_waitcnt lgkmcnt(0)
	s_setprio 1
	v_mfma_f32_16x16x32_bf16 v[128:131], v[148:151], v[164:167], v[128:131]
	v_mfma_f32_16x16x32_bf16 v[124:127], v[156:159], v[164:167], v[124:127]
	v_mfma_f32_16x16x32_bf16 v[120:123], v[148:151], v[172:175], v[120:123]
	v_mfma_f32_16x16x32_bf16 v[112:115], v[156:159], v[172:175], v[112:115]
	v_mfma_f32_16x16x32_bf16 v[104:107], v[148:151], v[194:197], v[104:107]
	v_mfma_f32_16x16x32_bf16 v[96:99], v[156:159], v[194:197], v[96:99]
	v_mfma_f32_16x16x32_bf16 v[84:87], v[148:151], v[202:205], v[84:87]
	v_mfma_f32_16x16x32_bf16 v[76:79], v[156:159], v[202:205], v[76:79]
	v_mfma_f32_16x16x32_bf16 v[128:131], v[152:155], v[168:171], v[128:131]
	v_mfma_f32_16x16x32_bf16 v[124:127], v[160:163], v[168:171], v[124:127]
	v_mfma_f32_16x16x32_bf16 v[120:123], v[152:155], v[176:179], v[120:123]
	v_mfma_f32_16x16x32_bf16 v[112:115], v[160:163], v[176:179], v[112:115]
	v_mfma_f32_16x16x32_bf16 v[104:107], v[152:155], v[198:201], v[104:107]
	v_mfma_f32_16x16x32_bf16 v[96:99], v[160:163], v[198:201], v[96:99]
	v_mfma_f32_16x16x32_bf16 v[84:87], v[152:155], v[206:209], v[84:87]
	v_mfma_f32_16x16x32_bf16 v[76:79], v[160:163], v[206:209], v[76:79]
	s_setprio 0
	s_barrier
	v_or_b32_e32 v142, 0x14000, v146
	v_add_u32_e32 v143, 0x14400, v146
	ds_read_b128 v[210:213], v142
	ds_read_b128 v[214:217], v143
	v_add_u32_e32 v142, 0x14800, v146
	v_add_u32_e32 v143, 0x14c00, v146
	s_mov_b32 m0, s21
	ds_read_b128 v[218:221], v142
	ds_read_b128 v[222:225], v143
	v_lshl_add_u64 v[142:143], s[14:15], 0, v[2:3]
	global_load_lds_dwordx4 v[142:143], off
	v_lshl_add_u64 v[240:241], s[14:15], 0, v[132:133]
	s_mov_b32 m0, s22
	s_nop 0
	global_load_lds_dwordx4 v[240:241], off
	s_barrier
	s_waitcnt lgkmcnt(0)
	s_setprio 1
	v_mfma_f32_16x16x32_bf16 v[116:119], v[210:213], v[164:167], v[116:119]
	v_mfma_f32_16x16x32_bf16 v[108:111], v[218:221], v[164:167], v[108:111]
	v_mfma_f32_16x16x32_bf16 v[100:103], v[210:213], v[172:175], v[100:103]
	v_mfma_f32_16x16x32_bf16 v[92:95], v[218:221], v[172:175], v[92:95]
	v_mfma_f32_16x16x32_bf16 v[88:91], v[210:213], v[194:197], v[88:91]
	v_mfma_f32_16x16x32_bf16 v[80:83], v[218:221], v[194:197], v[80:83]
	v_mfma_f32_16x16x32_bf16 v[72:75], v[210:213], v[202:205], v[72:75]
	v_mfma_f32_16x16x32_bf16 v[68:71], v[218:221], v[202:205], v[68:71]
	v_mfma_f32_16x16x32_bf16 v[116:119], v[214:217], v[168:171], v[116:119]
	v_mfma_f32_16x16x32_bf16 v[108:111], v[222:225], v[168:171], v[108:111]
	v_mfma_f32_16x16x32_bf16 v[100:103], v[214:217], v[176:179], v[100:103]
	v_mfma_f32_16x16x32_bf16 v[92:95], v[222:225], v[176:179], v[92:95]
	v_mfma_f32_16x16x32_bf16 v[88:91], v[214:217], v[198:201], v[88:91]
	v_mfma_f32_16x16x32_bf16 v[80:83], v[222:225], v[198:201], v[80:83]
	v_mfma_f32_16x16x32_bf16 v[72:75], v[214:217], v[206:209], v[72:75]
	v_mfma_f32_16x16x32_bf16 v[68:71], v[222:225], v[206:209], v[68:71]
	s_setprio 0
	s_mov_b32 m0, s20
	v_lshl_add_u64 v[242:243], s[16:17], 0, v[136:137]
	s_barrier
	ds_read_b128 v[164:167], v145 offset:16384
	ds_read_b128 v[168:171], v145 offset:17408
	ds_read_b128 v[172:175], v145 offset:18432
	ds_read_b128 v[176:179], v145 offset:19456
	ds_read_b128 v[194:197], v145 offset:20480
	ds_read_b128 v[198:201], v145 offset:21504
	ds_read_b128 v[202:205], v145 offset:22528
	ds_read_b128 v[206:209], v145 offset:23552
	global_load_lds_dwordx4 v[242:243], off
	v_lshl_add_u64 v[244:245], s[16:17], 0, v[134:135]
	s_mov_b32 m0, s23
	s_nop 0
	global_load_lds_dwordx4 v[244:245], off
	s_barrier
	s_waitcnt lgkmcnt(0)
	s_setprio 1
	v_mfma_f32_16x16x32_bf16 v[64:67], v[148:151], v[164:167], v[64:67]
	v_mfma_f32_16x16x32_bf16 v[60:63], v[156:159], v[164:167], v[60:63]
	v_mfma_f32_16x16x32_bf16 v[56:59], v[148:151], v[172:175], v[56:59]
	v_mfma_f32_16x16x32_bf16 v[48:51], v[156:159], v[172:175], v[48:51]
	v_mfma_f32_16x16x32_bf16 v[40:43], v[148:151], v[194:197], v[40:43]
	v_mfma_f32_16x16x32_bf16 v[32:35], v[156:159], v[194:197], v[32:35]
	v_mfma_f32_16x16x32_bf16 v[24:27], v[148:151], v[202:205], v[24:27]
	v_mfma_f32_16x16x32_bf16 v[16:19], v[156:159], v[202:205], v[16:19]
	v_mfma_f32_16x16x32_bf16 v[64:67], v[152:155], v[168:171], v[64:67]
	v_mfma_f32_16x16x32_bf16 v[60:63], v[160:163], v[168:171], v[60:63]
	v_mfma_f32_16x16x32_bf16 v[56:59], v[152:155], v[176:179], v[56:59]
	v_mfma_f32_16x16x32_bf16 v[48:51], v[160:163], v[176:179], v[48:51]
	v_mfma_f32_16x16x32_bf16 v[40:43], v[152:155], v[198:201], v[40:43]
	v_mfma_f32_16x16x32_bf16 v[32:35], v[160:163], v[198:201], v[32:35]
	v_mfma_f32_16x16x32_bf16 v[24:27], v[152:155], v[206:209], v[24:27]
	v_mfma_f32_16x16x32_bf16 v[16:19], v[160:163], v[206:209], v[16:19]
	s_setprio 0
	s_barrier
	s_add_u32 s46, s14, 0x40000
	s_addc_u32 s47, s15, 0
	s_mov_b32 m0, s24
	v_lshl_add_u64 v[148:149], s[46:47], 0, v[2:3]
	global_load_lds_dwordx4 v[148:149], off
	v_lshl_add_u64 v[148:149], s[46:47], 0, v[132:133]
	s_mov_b32 m0, s25
	s_nop 0
	global_load_lds_dwordx4 v[148:149], off
	s_waitcnt vmcnt(6)
	s_barrier
	s_setprio 1
	v_mfma_f32_16x16x32_bf16 v[52:55], v[210:213], v[164:167], v[52:55]
	v_mfma_f32_16x16x32_bf16 v[44:47], v[218:221], v[164:167], v[44:47]
	v_mfma_f32_16x16x32_bf16 v[36:39], v[210:213], v[172:175], v[36:39]
	v_mfma_f32_16x16x32_bf16 v[28:31], v[218:221], v[172:175], v[28:31]
	v_mfma_f32_16x16x32_bf16 v[20:23], v[210:213], v[194:197], v[20:23]
	v_mfma_f32_16x16x32_bf16 v[12:15], v[218:221], v[194:197], v[12:15]
	v_mfma_f32_16x16x32_bf16 v[8:11], v[210:213], v[202:205], v[8:11]
	v_mfma_f32_16x16x32_bf16 v[4:7], v[218:221], v[202:205], v[4:7]
	v_mfma_f32_16x16x32_bf16 v[52:55], v[214:217], v[168:171], v[52:55]
	v_mfma_f32_16x16x32_bf16 v[44:47], v[222:225], v[168:171], v[44:47]
	v_mfma_f32_16x16x32_bf16 v[36:39], v[214:217], v[176:179], v[36:39]
	v_mfma_f32_16x16x32_bf16 v[28:31], v[222:225], v[176:179], v[28:31]
	v_mfma_f32_16x16x32_bf16 v[20:23], v[214:217], v[198:201], v[20:23]
	v_mfma_f32_16x16x32_bf16 v[12:15], v[222:225], v[198:201], v[12:15]
	v_mfma_f32_16x16x32_bf16 v[8:11], v[214:217], v[206:209], v[8:11]
	v_mfma_f32_16x16x32_bf16 v[4:7], v[222:225], v[206:209], v[4:7]
	s_setprio 0
	v_or_b32_e32 v148, 0x18000, v146
	v_add_u32_e32 v152, 0x18400, v146
	v_add_u32_e32 v156, 0x18800, v146
	v_add_u32_e32 v160, 0x18c00, v146
	s_barrier
	ds_read_b128 v[148:151], v148
	ds_read_b128 v[152:155], v152
	ds_read_b128 v[156:159], v156
	ds_read_b128 v[160:163], v160
	s_add_u32 s16, s16, 0x40000
	s_addc_u32 s17, s17, 0
	s_mov_b32 m0, s26
	v_lshl_add_u64 v[210:211], s[16:17], 0, v[136:137]
	ds_read_b128 v[164:167], v145 offset:32768
	ds_read_b128 v[168:171], v145 offset:33792
	ds_read_b128 v[172:175], v145 offset:34816
	ds_read_b128 v[176:179], v145 offset:35840
	ds_read_b128 v[194:197], v145 offset:36864
	ds_read_b128 v[198:201], v145 offset:37888
	ds_read_b128 v[202:205], v145 offset:38912
	ds_read_b128 v[206:209], v145 offset:39936
	global_load_lds_dwordx4 v[210:211], off
	v_lshl_add_u64 v[210:211], s[16:17], 0, v[134:135]
	s_mov_b32 m0, s27
	s_nop 0
	global_load_lds_dwordx4 v[210:211], off
	s_waitcnt lgkmcnt(8)
	s_barrier
	s_waitcnt lgkmcnt(0)
	s_setprio 1
	v_mfma_f32_16x16x32_bf16 v[128:131], v[148:151], v[164:167], v[128:131]
	v_mfma_f32_16x16x32_bf16 v[124:127], v[156:159], v[164:167], v[124:127]
	v_mfma_f32_16x16x32_bf16 v[120:123], v[148:151], v[172:175], v[120:123]
	v_mfma_f32_16x16x32_bf16 v[112:115], v[156:159], v[172:175], v[112:115]
	v_mfma_f32_16x16x32_bf16 v[104:107], v[148:151], v[194:197], v[104:107]
	v_mfma_f32_16x16x32_bf16 v[96:99], v[156:159], v[194:197], v[96:99]
	v_mfma_f32_16x16x32_bf16 v[84:87], v[148:151], v[202:205], v[84:87]
	v_mfma_f32_16x16x32_bf16 v[76:79], v[156:159], v[202:205], v[76:79]
	v_mfma_f32_16x16x32_bf16 v[128:131], v[152:155], v[168:171], v[128:131]
	v_mfma_f32_16x16x32_bf16 v[124:127], v[160:163], v[168:171], v[124:127]
	v_mfma_f32_16x16x32_bf16 v[120:123], v[152:155], v[176:179], v[120:123]
	v_mfma_f32_16x16x32_bf16 v[112:115], v[160:163], v[176:179], v[112:115]
	v_mfma_f32_16x16x32_bf16 v[104:107], v[152:155], v[198:201], v[104:107]
	v_mfma_f32_16x16x32_bf16 v[96:99], v[160:163], v[198:201], v[96:99]
	v_mfma_f32_16x16x32_bf16 v[84:87], v[152:155], v[206:209], v[84:87]
	v_mfma_f32_16x16x32_bf16 v[76:79], v[160:163], v[206:209], v[76:79]
	s_setprio 0
	s_barrier
	v_or_b32_e32 v189, 0x1c000, v146
	v_add_u32_e32 v214, 0x1c400, v146
	s_mov_b32 m0, s29
	ds_read_b128 v[210:213], v189
	ds_read_b128 v[214:217], v214
	v_add_u32_e32 v189, 0x1c800, v146
	v_add_u32_e32 v222, 0x1cc00, v146
	v_lshl_add_u64 v[142:143], v[142:143], 0, s[82:83]
	ds_read_b128 v[218:221], v189
	ds_read_b128 v[222:225], v222
	global_load_lds_dwordx4 v[142:143], off
	v_lshl_add_u64 v[142:143], v[240:241], 0, s[82:83]
	s_mov_b32 m0, s30
	s_nop 0
	global_load_lds_dwordx4 v[142:143], off
	s_barrier
	s_waitcnt lgkmcnt(0)
	s_setprio 1
	v_mfma_f32_16x16x32_bf16 v[116:119], v[210:213], v[164:167], v[116:119]
	v_mfma_f32_16x16x32_bf16 v[108:111], v[218:221], v[164:167], v[108:111]
	v_mfma_f32_16x16x32_bf16 v[100:103], v[210:213], v[172:175], v[100:103]
	v_mfma_f32_16x16x32_bf16 v[92:95], v[218:221], v[172:175], v[92:95]
	v_mfma_f32_16x16x32_bf16 v[88:91], v[210:213], v[194:197], v[88:91]
	v_mfma_f32_16x16x32_bf16 v[80:83], v[218:221], v[194:197], v[80:83]
	v_mfma_f32_16x16x32_bf16 v[72:75], v[210:213], v[202:205], v[72:75]
	v_mfma_f32_16x16x32_bf16 v[68:71], v[218:221], v[202:205], v[68:71]
	v_mfma_f32_16x16x32_bf16 v[116:119], v[214:217], v[168:171], v[116:119]
	v_mfma_f32_16x16x32_bf16 v[108:111], v[222:225], v[168:171], v[108:111]
	v_mfma_f32_16x16x32_bf16 v[100:103], v[214:217], v[176:179], v[100:103]
	v_mfma_f32_16x16x32_bf16 v[92:95], v[222:225], v[176:179], v[92:95]
	v_mfma_f32_16x16x32_bf16 v[88:91], v[214:217], v[198:201], v[88:91]
	v_mfma_f32_16x16x32_bf16 v[80:83], v[222:225], v[198:201], v[80:83]
	v_mfma_f32_16x16x32_bf16 v[72:75], v[214:217], v[206:209], v[72:75]
	v_mfma_f32_16x16x32_bf16 v[68:71], v[222:225], v[206:209], v[68:71]
	s_setprio 0
	s_mov_b32 m0, s31
	v_lshl_add_u64 v[142:143], v[242:243], 0, s[82:83]
	s_barrier
	ds_read_b128 v[164:167], v145 offset:49152
	ds_read_b128 v[168:171], v145 offset:50176
	ds_read_b128 v[172:175], v145 offset:51200
	ds_read_b128 v[176:179], v145 offset:52224
	ds_read_b128 v[194:197], v145 offset:53248
	ds_read_b128 v[198:201], v145 offset:54272
	ds_read_b128 v[202:205], v145 offset:55296
	ds_read_b128 v[206:209], v145 offset:56320
	global_load_lds_dwordx4 v[142:143], off
	v_lshl_add_u64 v[142:143], v[244:245], 0, s[82:83]
	s_mov_b32 m0, s34
	s_nop 0
	global_load_lds_dwordx4 v[142:143], off
	s_barrier
	s_waitcnt lgkmcnt(0)
	s_setprio 1
	v_mfma_f32_16x16x32_bf16 v[64:67], v[148:151], v[164:167], v[64:67]
	v_mfma_f32_16x16x32_bf16 v[60:63], v[156:159], v[164:167], v[60:63]
	v_mfma_f32_16x16x32_bf16 v[56:59], v[148:151], v[172:175], v[56:59]
	v_mfma_f32_16x16x32_bf16 v[48:51], v[156:159], v[172:175], v[48:51]
	v_mfma_f32_16x16x32_bf16 v[40:43], v[148:151], v[194:197], v[40:43]
	v_mfma_f32_16x16x32_bf16 v[32:35], v[156:159], v[194:197], v[32:35]
	v_mfma_f32_16x16x32_bf16 v[24:27], v[148:151], v[202:205], v[24:27]
	v_mfma_f32_16x16x32_bf16 v[16:19], v[156:159], v[202:205], v[16:19]
	v_mfma_f32_16x16x32_bf16 v[64:67], v[152:155], v[168:171], v[64:67]
	v_mfma_f32_16x16x32_bf16 v[60:63], v[160:163], v[168:171], v[60:63]
	v_mfma_f32_16x16x32_bf16 v[56:59], v[152:155], v[176:179], v[56:59]
	v_mfma_f32_16x16x32_bf16 v[48:51], v[160:163], v[176:179], v[48:51]
	v_mfma_f32_16x16x32_bf16 v[40:43], v[152:155], v[198:201], v[40:43]
	v_mfma_f32_16x16x32_bf16 v[32:35], v[160:163], v[198:201], v[32:35]
	v_mfma_f32_16x16x32_bf16 v[24:27], v[152:155], v[206:209], v[24:27]
	v_mfma_f32_16x16x32_bf16 v[16:19], v[160:163], v[206:209], v[16:19]
	s_setprio 0
	s_barrier
	s_add_u32 s14, s14, 0x40080
	s_addc_u32 s15, s15, 0
	s_mov_b32 m0, s35
	v_lshl_add_u64 v[142:143], s[14:15], 0, v[2:3]
	global_load_lds_dwordx4 v[142:143], off
	v_lshl_add_u64 v[142:143], s[14:15], 0, v[132:133]
	s_mov_b32 m0, s36
	s_nop 0
	global_load_lds_dwordx4 v[142:143], off
	s_waitcnt vmcnt(6)
	s_barrier
	s_setprio 1
	v_mfma_f32_16x16x32_bf16 v[52:55], v[210:213], v[164:167], v[52:55]
	v_mfma_f32_16x16x32_bf16 v[44:47], v[218:221], v[164:167], v[44:47]
	v_mfma_f32_16x16x32_bf16 v[36:39], v[210:213], v[172:175], v[36:39]
	v_mfma_f32_16x16x32_bf16 v[28:31], v[218:221], v[172:175], v[28:31]
	v_mfma_f32_16x16x32_bf16 v[20:23], v[210:213], v[194:197], v[20:23]
	v_mfma_f32_16x16x32_bf16 v[12:15], v[218:221], v[194:197], v[12:15]
	v_mfma_f32_16x16x32_bf16 v[8:11], v[210:213], v[202:205], v[8:11]
	v_mfma_f32_16x16x32_bf16 v[4:7], v[218:221], v[202:205], v[4:7]
	v_mfma_f32_16x16x32_bf16 v[52:55], v[214:217], v[168:171], v[52:55]
	v_mfma_f32_16x16x32_bf16 v[44:47], v[222:225], v[168:171], v[44:47]
	v_mfma_f32_16x16x32_bf16 v[36:39], v[214:217], v[176:179], v[36:39]
	v_mfma_f32_16x16x32_bf16 v[28:31], v[222:225], v[176:179], v[28:31]
	v_mfma_f32_16x16x32_bf16 v[20:23], v[214:217], v[198:201], v[20:23]
	v_mfma_f32_16x16x32_bf16 v[12:15], v[222:225], v[198:201], v[12:15]
	v_mfma_f32_16x16x32_bf16 v[8:11], v[214:217], v[206:209], v[8:11]
	v_mfma_f32_16x16x32_bf16 v[4:7], v[222:225], v[206:209], v[4:7]
	s_setprio 0
	s_add_i32 s45, s45, 2
	s_add_u32 s12, s12, 0x100
	s_addc_u32 s13, s13, 0
	s_add_u32 s43, s43, 0x100
	s_addc_u32 s44, s44, 0
	s_cmp_gt_u32 s45, 13
	s_barrier
	s_cbranch_scc0 .LBB0_292
	v_lshl_add_u32 v148, s40, 8, v144
	v_lshl_or_b32 v142, s39, 8, v147
	v_ashrrev_i32_e32 v149, 31, v148
	v_readlane_b32 s12, v253, 26
	v_ashrrev_i32_e32 v143, 31, v142
	v_lshlrev_b64 v[150:151], 11, v[148:149]
	v_readlane_b32 s13, v253, 27
	v_lshlrev_b64 v[152:153], 1, v[142:143]
	v_cvt_pk_bf16_f32 v128, v128, v129
	v_cvt_pk_bf16_f32 v129, v130, v131
	v_cvt_pk_bf16_f32 v130, v124, v125
	v_cvt_pk_bf16_f32 v131, v126, v127
	s_nop 0
	v_lshl_add_u64 v[150:151], s[12:13], 0, v[150:151]
	v_lshl_add_u64 v[142:143], v[150:151], 0, v[152:153]
	global_store_dwordx4 v[142:143], v[128:131], off sc1
	v_cvt_pk_bf16_f32 v116, v116, v117
	v_cvt_pk_bf16_f32 v117, v118, v119
	v_cvt_pk_bf16_f32 v118, v108, v109
	v_or_b32_e32 v108, 16, v148
	v_ashrrev_i32_e32 v109, 31, v108
	v_lshlrev_b64 v[108:109], 11, v[108:109]
	v_lshl_add_u64 v[108:109], s[12:13], 0, v[108:109]
	v_cvt_pk_bf16_f32 v119, v110, v111
	global_store_dwordx4 v[142:143], v[116:119], off offset:256 sc1
	s_mov_b32 s5, 0x40000
	s_mov_b32 s39, s4
	v_lshl_add_u64 v[116:117], v[108:109], 0, v[152:153]
	v_cvt_pk_bf16_f32 v108, v120, v121
	v_cvt_pk_bf16_f32 v109, v122, v123
	v_cvt_pk_bf16_f32 v110, v112, v113
	v_cvt_pk_bf16_f32 v111, v114, v115
	global_store_dwordx4 v[116:117], v[108:111], off sc1
	v_cvt_pk_bf16_f32 v100, v100, v101
	v_cvt_pk_bf16_f32 v101, v102, v103
	v_cvt_pk_bf16_f32 v102, v92, v93
	v_or_b32_e32 v92, 32, v148
	v_ashrrev_i32_e32 v93, 31, v92
	v_lshlrev_b64 v[92:93], 11, v[92:93]
	v_lshl_add_u64 v[92:93], s[12:13], 0, v[92:93]
	v_cvt_pk_bf16_f32 v103, v94, v95
	global_store_dwordx4 v[116:117], v[100:103], off offset:256 sc1
	s_mov_b32 s40, s6
	s_mov_b64 s[14:15], s[10:11]
	v_lshl_add_u64 v[100:101], v[92:93], 0, v[152:153]
	v_cvt_pk_bf16_f32 v92, v104, v105
	v_cvt_pk_bf16_f32 v93, v106, v107
	v_cvt_pk_bf16_f32 v94, v96, v97
	v_cvt_pk_bf16_f32 v95, v98, v99
	global_store_dwordx4 v[100:101], v[92:95], off sc1
	v_cvt_pk_bf16_f32 v88, v88, v89
	v_cvt_pk_bf16_f32 v89, v90, v91
	v_cvt_pk_bf16_f32 v90, v80, v81
	v_or_b32_e32 v80, 48, v148
	v_ashrrev_i32_e32 v81, 31, v80
	v_lshlrev_b64 v[80:81], 11, v[80:81]
	v_lshl_add_u64 v[80:81], s[12:13], 0, v[80:81]
	v_cvt_pk_bf16_f32 v91, v82, v83
	global_store_dwordx4 v[100:101], v[88:91], off offset:256 sc1
	s_mov_b64 s[12:13], 0x40000
	s_nop 0
	v_lshl_add_u64 v[88:89], v[80:81], 0, v[152:153]
	v_cvt_pk_bf16_f32 v80, v84, v85
	v_cvt_pk_bf16_f32 v81, v86, v87
	v_cvt_pk_bf16_f32 v82, v76, v77
	v_cvt_pk_bf16_f32 v83, v78, v79
	global_store_dwordx4 v[88:89], v[80:83], off sc1
	v_cvt_pk_bf16_f32 v72, v72, v73
	v_cvt_pk_bf16_f32 v73, v74, v75
	v_cvt_pk_bf16_f32 v74, v68, v69
	v_cvt_pk_bf16_f32 v75, v70, v71
	global_store_dwordx4 v[88:89], v[72:75], off offset:256 sc1
	v_cvt_pk_bf16_f32 v64, v64, v65
	v_cvt_pk_bf16_f32 v65, v66, v67
	v_cvt_pk_bf16_f32 v66, v60, v61
	v_add_co_u32_e32 v60, vcc, s5, v142
	v_lshl_add_u64 v[68:69], v[142:143], 0, s[12:13]
	s_nop 0
	v_addc_co_u32_e32 v61, vcc, 0, v143, vcc
	s_mov_b32 s5, 0x48000
	v_cvt_pk_bf16_f32 v67, v62, v63
	global_store_dwordx4 v[60:61], v[64:67], off sc1
	v_cvt_pk_bf16_f32 v52, v52, v53
	v_cvt_pk_bf16_f32 v53, v54, v55
	v_cvt_pk_bf16_f32 v54, v44, v45
	v_cvt_pk_bf16_f32 v55, v46, v47
	global_store_dwordx4 v[68:69], v[52:55], off offset:256 sc1
	s_mov_b64 s[12:13], 0x48000
	v_cvt_pk_bf16_f32 v44, v56, v57
	v_cvt_pk_bf16_f32 v45, v58, v59
	v_cvt_pk_bf16_f32 v46, v48, v49
	v_add_co_u32_e32 v48, vcc, s5, v142
	v_lshl_add_u64 v[52:53], v[142:143], 0, s[12:13]
	s_nop 0
	v_addc_co_u32_e32 v49, vcc, 0, v143, vcc
	s_mov_b32 s5, 0x50000
	v_cvt_pk_bf16_f32 v47, v50, v51
	global_store_dwordx4 v[48:49], v[44:47], off sc1
	v_cvt_pk_bf16_f32 v36, v36, v37
	v_cvt_pk_bf16_f32 v37, v38, v39
	v_cvt_pk_bf16_f32 v38, v28, v29
	v_cvt_pk_bf16_f32 v39, v30, v31
	global_store_dwordx4 v[52:53], v[36:39], off offset:256 sc1
	s_mov_b64 s[12:13], 0x50000
	v_cvt_pk_bf16_f32 v28, v40, v41
	v_cvt_pk_bf16_f32 v29, v42, v43
	v_cvt_pk_bf16_f32 v30, v32, v33
	v_add_co_u32_e32 v32, vcc, s5, v142
	v_lshl_add_u64 v[36:37], v[142:143], 0, s[12:13]
	s_nop 0
	v_addc_co_u32_e32 v33, vcc, 0, v143, vcc
	s_mov_b32 s5, 0x58000
	v_cvt_pk_bf16_f32 v31, v34, v35
	global_store_dwordx4 v[32:33], v[28:31], off sc1
	v_cvt_pk_bf16_f32 v20, v20, v21
	v_cvt_pk_bf16_f32 v21, v22, v23
	v_cvt_pk_bf16_f32 v22, v12, v13
	v_cvt_pk_bf16_f32 v23, v14, v15
	global_store_dwordx4 v[36:37], v[20:23], off offset:256 sc1
	v_cvt_pk_bf16_f32 v12, v24, v25
	v_cvt_pk_bf16_f32 v13, v26, v27
	v_cvt_pk_bf16_f32 v14, v16, v17
	v_add_co_u32_e32 v16, vcc, s5, v142
	s_mov_b64 s[12:13], 0x58000
	s_nop 0
	v_addc_co_u32_e32 v17, vcc, 0, v143, vcc
	v_lshl_add_u64 v[20:21], v[142:143], 0, s[12:13]
	s_and_b64 vcc, exec, s[2:3]
	s_mov_b64 s[12:13], s[8:9]
	v_cvt_pk_bf16_f32 v15, v18, v19
	global_store_dwordx4 v[16:17], v[12:15], off sc1
	v_cvt_pk_bf16_f32 v8, v8, v9
	v_cvt_pk_bf16_f32 v9, v10, v11
	v_cvt_pk_bf16_f32 v10, v4, v5
	v_cvt_pk_bf16_f32 v11, v6, v7
	global_store_dwordx4 v[20:21], v[8:11], off offset:256 sc1
	s_cbranch_vccz .LBB0_285
	s_waitcnt vmcnt(0)
	s_cmpk_gt_u32 s0, 0xff
	v_readlane_b32 s34, v251, 48
	s_cbranch_scc1 .LBB0_296
	s_barrier

.LBB0_655:
	v_or_b32_e32 v142, 0x10000, v148
	v_add_u32_e32 v150, 0x10400, v148
	v_add_u32_e32 v154, 0x10800, v148
	v_add_u32_e32 v158, 0x10c00, v148
	ds_read_b128 v[142:145], v142
	ds_read_b128 v[150:153], v150
	ds_read_b128 v[154:157], v154
	ds_read_b128 v[158:161], v158
	s_add_u32 s14, s12, 0xfffc0080
	s_addc_u32 s15, s13, -1
	s_cmp_eq_u32 s45, 12
	s_cselect_b32 s17, s7, s15
	s_cselect_b32 s16, s41, s14
	s_cselect_b32 s15, s5, s44
	s_cselect_b32 s14, s42, s43
	v_lshl_add_u64 v[178:179], s[12:13], 0, v[138:139]
	s_add_i32 m0, s20, 0xc000
	ds_read_b128 v[162:165], v147
	ds_read_b128 v[166:169], v147 offset:1024
	ds_read_b128 v[170:173], v147 offset:2048
	ds_read_b128 v[174:177], v147 offset:3072
	ds_read_b128 v[194:197], v147 offset:4096
	ds_read_b128 v[198:201], v147 offset:5120
	ds_read_b128 v[202:205], v147 offset:6144
	ds_read_b128 v[206:209], v147 offset:7168
	global_load_lds_dwordx4 v[178:179], off
	v_lshl_add_u64 v[178:179], s[12:13], 0, v[140:141]
	s_add_i32 m0, s20, 0xe000
	s_nop 0
	global_load_lds_dwordx4 v[178:179], off
	s_waitcnt lgkmcnt(8)
	s_barrier
	s_waitcnt lgkmcnt(0)
	s_setprio 1
	v_mfma_f32_16x16x32_bf16 v[128:131], v[142:145], v[162:165], v[128:131]
	v_mfma_f32_16x16x32_bf16 v[124:127], v[154:157], v[162:165], v[124:127]
	v_mfma_f32_16x16x32_bf16 v[120:123], v[142:145], v[170:173], v[120:123]
	v_mfma_f32_16x16x32_bf16 v[112:115], v[154:157], v[170:173], v[112:115]
	v_mfma_f32_16x16x32_bf16 v[104:107], v[142:145], v[194:197], v[104:107]
	v_mfma_f32_16x16x32_bf16 v[96:99], v[154:157], v[194:197], v[96:99]
	v_mfma_f32_16x16x32_bf16 v[88:91], v[142:145], v[202:205], v[88:91]
	v_mfma_f32_16x16x32_bf16 v[80:83], v[154:157], v[202:205], v[80:83]
	v_mfma_f32_16x16x32_bf16 v[128:131], v[150:153], v[166:169], v[128:131]
	v_mfma_f32_16x16x32_bf16 v[124:127], v[158:161], v[166:169], v[124:127]
	v_mfma_f32_16x16x32_bf16 v[120:123], v[150:153], v[174:177], v[120:123]
	v_mfma_f32_16x16x32_bf16 v[112:115], v[158:161], v[174:177], v[112:115]
	v_mfma_f32_16x16x32_bf16 v[104:107], v[150:153], v[198:201], v[104:107]
	v_mfma_f32_16x16x32_bf16 v[96:99], v[158:161], v[198:201], v[96:99]
	v_mfma_f32_16x16x32_bf16 v[88:91], v[150:153], v[206:209], v[88:91]
	v_mfma_f32_16x16x32_bf16 v[80:83], v[158:161], v[206:209], v[80:83]
	s_setprio 0
	s_barrier
	v_or_b32_e32 v178, 0x14000, v148
	v_add_u32_e32 v179, 0x14400, v148
	ds_read_b128 v[210:213], v178
	ds_read_b128 v[214:217], v179
	v_add_u32_e32 v178, 0x14800, v148
	v_add_u32_e32 v179, 0x14c00, v148
	s_mov_b32 m0, s21
	ds_read_b128 v[218:221], v178
	ds_read_b128 v[222:225], v179
	v_lshl_add_u64 v[178:179], s[14:15], 0, v[2:3]
	global_load_lds_dwordx4 v[178:179], off
	v_lshl_add_u64 v[240:241], s[14:15], 0, v[132:133]
	s_mov_b32 m0, s22
	s_nop 0
	global_load_lds_dwordx4 v[240:241], off
	s_barrier
	s_waitcnt lgkmcnt(0)
	s_setprio 1
	v_mfma_f32_16x16x32_bf16 v[116:119], v[210:213], v[162:165], v[116:119]
	v_mfma_f32_16x16x32_bf16 v[108:111], v[218:221], v[162:165], v[108:111]
	v_mfma_f32_16x16x32_bf16 v[100:103], v[210:213], v[170:173], v[100:103]
	v_mfma_f32_16x16x32_bf16 v[92:95], v[218:221], v[170:173], v[92:95]
	v_mfma_f32_16x16x32_bf16 v[84:87], v[210:213], v[194:197], v[84:87]
	v_mfma_f32_16x16x32_bf16 v[76:79], v[218:221], v[194:197], v[76:79]
	v_mfma_f32_16x16x32_bf16 v[72:75], v[210:213], v[202:205], v[72:75]
	v_mfma_f32_16x16x32_bf16 v[68:71], v[218:221], v[202:205], v[68:71]
	v_mfma_f32_16x16x32_bf16 v[116:119], v[214:217], v[166:169], v[116:119]
	v_mfma_f32_16x16x32_bf16 v[108:111], v[222:225], v[166:169], v[108:111]
	v_mfma_f32_16x16x32_bf16 v[100:103], v[214:217], v[174:177], v[100:103]
	v_mfma_f32_16x16x32_bf16 v[92:95], v[222:225], v[174:177], v[92:95]
	v_mfma_f32_16x16x32_bf16 v[84:87], v[214:217], v[198:201], v[84:87]
	v_mfma_f32_16x16x32_bf16 v[76:79], v[222:225], v[198:201], v[76:79]
	v_mfma_f32_16x16x32_bf16 v[72:75], v[214:217], v[206:209], v[72:75]
	v_mfma_f32_16x16x32_bf16 v[68:71], v[222:225], v[206:209], v[68:71]
	s_setprio 0
	s_mov_b32 m0, s20
	v_lshl_add_u64 v[242:243], s[16:17], 0, v[136:137]
	s_barrier
	ds_read_b128 v[162:165], v147 offset:16384
	ds_read_b128 v[166:169], v147 offset:17408
	ds_read_b128 v[170:173], v147 offset:18432
	ds_read_b128 v[174:177], v147 offset:19456
	ds_read_b128 v[194:197], v147 offset:20480
	ds_read_b128 v[198:201], v147 offset:21504
	ds_read_b128 v[202:205], v147 offset:22528
	ds_read_b128 v[206:209], v147 offset:23552
	global_load_lds_dwordx4 v[242:243], off
	v_lshl_add_u64 v[244:245], s[16:17], 0, v[134:135]
	s_mov_b32 m0, s23
	s_nop 0
	global_load_lds_dwordx4 v[244:245], off
	s_barrier
	s_waitcnt lgkmcnt(0)
	s_setprio 1
	v_mfma_f32_16x16x32_bf16 v[64:67], v[142:145], v[162:165], v[64:67]
	v_mfma_f32_16x16x32_bf16 v[60:63], v[154:157], v[162:165], v[60:63]
	v_mfma_f32_16x16x32_bf16 v[56:59], v[142:145], v[170:173], v[56:59]
	v_mfma_f32_16x16x32_bf16 v[48:51], v[154:157], v[170:173], v[48:51]
	v_mfma_f32_16x16x32_bf16 v[40:43], v[142:145], v[194:197], v[40:43]
	v_mfma_f32_16x16x32_bf16 v[32:35], v[154:157], v[194:197], v[32:35]
	v_mfma_f32_16x16x32_bf16 v[24:27], v[142:145], v[202:205], v[24:27]
	v_mfma_f32_16x16x32_bf16 v[16:19], v[154:157], v[202:205], v[16:19]
	v_mfma_f32_16x16x32_bf16 v[64:67], v[150:153], v[166:169], v[64:67]
	v_mfma_f32_16x16x32_bf16 v[60:63], v[158:161], v[166:169], v[60:63]
	v_mfma_f32_16x16x32_bf16 v[56:59], v[150:153], v[174:177], v[56:59]
	v_mfma_f32_16x16x32_bf16 v[48:51], v[158:161], v[174:177], v[48:51]
	v_mfma_f32_16x16x32_bf16 v[40:43], v[150:153], v[198:201], v[40:43]
	v_mfma_f32_16x16x32_bf16 v[32:35], v[158:161], v[198:201], v[32:35]
	v_mfma_f32_16x16x32_bf16 v[24:27], v[150:153], v[206:209], v[24:27]
	v_mfma_f32_16x16x32_bf16 v[16:19], v[158:161], v[206:209], v[16:19]
	s_setprio 0
	s_barrier
	s_add_u32 s46, s14, 0x40000
	s_addc_u32 s47, s15, 0
	s_mov_b32 m0, s24
	v_lshl_add_u64 v[142:143], s[46:47], 0, v[2:3]
	global_load_lds_dwordx4 v[142:143], off
	v_lshl_add_u64 v[142:143], s[46:47], 0, v[132:133]
	s_mov_b32 m0, s25
	s_nop 0
	global_load_lds_dwordx4 v[142:143], off
	s_waitcnt vmcnt(6)
	s_barrier
	s_setprio 1
	v_mfma_f32_16x16x32_bf16 v[52:55], v[210:213], v[162:165], v[52:55]
	v_mfma_f32_16x16x32_bf16 v[44:47], v[218:221], v[162:165], v[44:47]
	v_mfma_f32_16x16x32_bf16 v[36:39], v[210:213], v[170:173], v[36:39]
	v_mfma_f32_16x16x32_bf16 v[28:31], v[218:221], v[170:173], v[28:31]
	v_mfma_f32_16x16x32_bf16 v[20:23], v[210:213], v[194:197], v[20:23]
	v_mfma_f32_16x16x32_bf16 v[12:15], v[218:221], v[194:197], v[12:15]
	v_mfma_f32_16x16x32_bf16 v[8:11], v[210:213], v[202:205], v[8:11]
	v_mfma_f32_16x16x32_bf16 v[4:7], v[218:221], v[202:205], v[4:7]
	v_mfma_f32_16x16x32_bf16 v[52:55], v[214:217], v[166:169], v[52:55]
	v_mfma_f32_16x16x32_bf16 v[44:47], v[222:225], v[166:169], v[44:47]
	v_mfma_f32_16x16x32_bf16 v[36:39], v[214:217], v[174:177], v[36:39]
	v_mfma_f32_16x16x32_bf16 v[28:31], v[222:225], v[174:177], v[28:31]
	v_mfma_f32_16x16x32_bf16 v[20:23], v[214:217], v[198:201], v[20:23]
	v_mfma_f32_16x16x32_bf16 v[12:15], v[222:225], v[198:201], v[12:15]
	v_mfma_f32_16x16x32_bf16 v[8:11], v[214:217], v[206:209], v[8:11]
	v_mfma_f32_16x16x32_bf16 v[4:7], v[222:225], v[206:209], v[4:7]
	s_setprio 0
	v_or_b32_e32 v142, 0x18000, v148
	v_add_u32_e32 v150, 0x18400, v148
	v_add_u32_e32 v154, 0x18800, v148
	v_add_u32_e32 v158, 0x18c00, v148
	s_barrier
	ds_read_b128 v[142:145], v142
	ds_read_b128 v[150:153], v150
	ds_read_b128 v[154:157], v154
	ds_read_b128 v[158:161], v158
	s_add_u32 s16, s16, 0x40000
	s_addc_u32 s17, s17, 0
	s_mov_b32 m0, s26
	v_lshl_add_u64 v[210:211], s[16:17], 0, v[136:137]
	ds_read_b128 v[162:165], v147 offset:32768
	ds_read_b128 v[166:169], v147 offset:33792
	ds_read_b128 v[170:173], v147 offset:34816
	ds_read_b128 v[174:177], v147 offset:35840
	ds_read_b128 v[194:197], v147 offset:36864
	ds_read_b128 v[198:201], v147 offset:37888
	ds_read_b128 v[202:205], v147 offset:38912
	ds_read_b128 v[206:209], v147 offset:39936
	global_load_lds_dwordx4 v[210:211], off
	v_lshl_add_u64 v[210:211], s[16:17], 0, v[134:135]
	s_mov_b32 m0, s27
	s_nop 0
	global_load_lds_dwordx4 v[210:211], off
	s_waitcnt lgkmcnt(8)
	s_barrier
	s_waitcnt lgkmcnt(0)
	s_setprio 1
	v_mfma_f32_16x16x32_bf16 v[128:131], v[142:145], v[162:165], v[128:131]
	v_mfma_f32_16x16x32_bf16 v[124:127], v[154:157], v[162:165], v[124:127]
	v_mfma_f32_16x16x32_bf16 v[120:123], v[142:145], v[170:173], v[120:123]
	v_mfma_f32_16x16x32_bf16 v[112:115], v[154:157], v[170:173], v[112:115]
	v_mfma_f32_16x16x32_bf16 v[104:107], v[142:145], v[194:197], v[104:107]
	v_mfma_f32_16x16x32_bf16 v[96:99], v[154:157], v[194:197], v[96:99]
	v_mfma_f32_16x16x32_bf16 v[88:91], v[142:145], v[202:205], v[88:91]
	v_mfma_f32_16x16x32_bf16 v[80:83], v[154:157], v[202:205], v[80:83]
	v_mfma_f32_16x16x32_bf16 v[128:131], v[150:153], v[166:169], v[128:131]
	v_mfma_f32_16x16x32_bf16 v[124:127], v[158:161], v[166:169], v[124:127]
	v_mfma_f32_16x16x32_bf16 v[120:123], v[150:153], v[174:177], v[120:123]
	v_mfma_f32_16x16x32_bf16 v[112:115], v[158:161], v[174:177], v[112:115]
	v_mfma_f32_16x16x32_bf16 v[104:107], v[150:153], v[198:201], v[104:107]
	v_mfma_f32_16x16x32_bf16 v[96:99], v[158:161], v[198:201], v[96:99]
	v_mfma_f32_16x16x32_bf16 v[88:91], v[150:153], v[206:209], v[88:91]
	v_mfma_f32_16x16x32_bf16 v[80:83], v[158:161], v[206:209], v[80:83]
	s_setprio 0
	s_barrier
	v_or_b32_e32 v189, 0x1c000, v148
	v_add_u32_e32 v214, 0x1c400, v148
	s_mov_b32 m0, s28
	ds_read_b128 v[210:213], v189
	ds_read_b128 v[214:217], v214
	v_add_u32_e32 v189, 0x1c800, v148
	v_add_u32_e32 v222, 0x1cc00, v148
	v_lshl_add_u64 v[178:179], v[178:179], 0, s[82:83]
	ds_read_b128 v[218:221], v189
	ds_read_b128 v[222:225], v222
	global_load_lds_dwordx4 v[178:179], off
	v_lshl_add_u64 v[178:179], v[240:241], 0, s[82:83]
	s_mov_b32 m0, s29
	s_nop 0
	global_load_lds_dwordx4 v[178:179], off
	s_barrier
	s_waitcnt lgkmcnt(0)
	s_setprio 1
	v_mfma_f32_16x16x32_bf16 v[116:119], v[210:213], v[162:165], v[116:119]
	v_mfma_f32_16x16x32_bf16 v[108:111], v[218:221], v[162:165], v[108:111]
	v_mfma_f32_16x16x32_bf16 v[100:103], v[210:213], v[170:173], v[100:103]
	v_mfma_f32_16x16x32_bf16 v[92:95], v[218:221], v[170:173], v[92:95]
	v_mfma_f32_16x16x32_bf16 v[84:87], v[210:213], v[194:197], v[84:87]
	v_mfma_f32_16x16x32_bf16 v[76:79], v[218:221], v[194:197], v[76:79]
	v_mfma_f32_16x16x32_bf16 v[72:75], v[210:213], v[202:205], v[72:75]
	v_mfma_f32_16x16x32_bf16 v[68:71], v[218:221], v[202:205], v[68:71]
	v_mfma_f32_16x16x32_bf16 v[116:119], v[214:217], v[166:169], v[116:119]
	v_mfma_f32_16x16x32_bf16 v[108:111], v[222:225], v[166:169], v[108:111]
	v_mfma_f32_16x16x32_bf16 v[100:103], v[214:217], v[174:177], v[100:103]
	v_mfma_f32_16x16x32_bf16 v[92:95], v[222:225], v[174:177], v[92:95]
	v_mfma_f32_16x16x32_bf16 v[84:87], v[214:217], v[198:201], v[84:87]
	v_mfma_f32_16x16x32_bf16 v[76:79], v[222:225], v[198:201], v[76:79]
	v_mfma_f32_16x16x32_bf16 v[72:75], v[214:217], v[206:209], v[72:75]
	v_mfma_f32_16x16x32_bf16 v[68:71], v[222:225], v[206:209], v[68:71]
	s_setprio 0
	s_mov_b32 m0, s30
	v_lshl_add_u64 v[178:179], v[242:243], 0, s[82:83]
	s_barrier
	ds_read_b128 v[162:165], v147 offset:49152
	ds_read_b128 v[166:169], v147 offset:50176
	ds_read_b128 v[170:173], v147 offset:51200
	ds_read_b128 v[174:177], v147 offset:52224
	ds_read_b128 v[194:197], v147 offset:53248
	ds_read_b128 v[198:201], v147 offset:54272
	ds_read_b128 v[202:205], v147 offset:55296
	ds_read_b128 v[206:209], v147 offset:56320
	global_load_lds_dwordx4 v[178:179], off
	v_lshl_add_u64 v[178:179], v[244:245], 0, s[82:83]
	s_mov_b32 m0, s31
	s_nop 0
	global_load_lds_dwordx4 v[178:179], off
	s_barrier
	s_waitcnt lgkmcnt(0)
	s_setprio 1
	v_mfma_f32_16x16x32_bf16 v[64:67], v[142:145], v[162:165], v[64:67]
	v_mfma_f32_16x16x32_bf16 v[60:63], v[154:157], v[162:165], v[60:63]
	v_mfma_f32_16x16x32_bf16 v[56:59], v[142:145], v[170:173], v[56:59]
	v_mfma_f32_16x16x32_bf16 v[48:51], v[154:157], v[170:173], v[48:51]
	v_mfma_f32_16x16x32_bf16 v[40:43], v[142:145], v[194:197], v[40:43]
	v_mfma_f32_16x16x32_bf16 v[32:35], v[154:157], v[194:197], v[32:35]
	v_mfma_f32_16x16x32_bf16 v[24:27], v[142:145], v[202:205], v[24:27]
	v_mfma_f32_16x16x32_bf16 v[16:19], v[154:157], v[202:205], v[16:19]
	v_mfma_f32_16x16x32_bf16 v[64:67], v[150:153], v[166:169], v[64:67]
	v_mfma_f32_16x16x32_bf16 v[60:63], v[158:161], v[166:169], v[60:63]
	v_mfma_f32_16x16x32_bf16 v[56:59], v[150:153], v[174:177], v[56:59]
	v_mfma_f32_16x16x32_bf16 v[48:51], v[158:161], v[174:177], v[48:51]
	v_mfma_f32_16x16x32_bf16 v[40:43], v[150:153], v[198:201], v[40:43]
	v_mfma_f32_16x16x32_bf16 v[32:35], v[158:161], v[198:201], v[32:35]
	v_mfma_f32_16x16x32_bf16 v[24:27], v[150:153], v[206:209], v[24:27]
	v_mfma_f32_16x16x32_bf16 v[16:19], v[158:161], v[206:209], v[16:19]
	s_setprio 0
	s_barrier
	s_add_u32 s14, s14, 0x40080
	s_addc_u32 s15, s15, 0
	s_mov_b32 m0, s34
	v_lshl_add_u64 v[142:143], s[14:15], 0, v[2:3]
	global_load_lds_dwordx4 v[142:143], off
	v_lshl_add_u64 v[142:143], s[14:15], 0, v[132:133]
	s_mov_b32 m0, s35
	s_nop 0
	global_load_lds_dwordx4 v[142:143], off
	s_waitcnt vmcnt(6)
	s_barrier
	s_setprio 1
	v_mfma_f32_16x16x32_bf16 v[52:55], v[210:213], v[162:165], v[52:55]
	v_mfma_f32_16x16x32_bf16 v[44:47], v[218:221], v[162:165], v[44:47]
	v_mfma_f32_16x16x32_bf16 v[36:39], v[210:213], v[170:173], v[36:39]
	v_mfma_f32_16x16x32_bf16 v[28:31], v[218:221], v[170:173], v[28:31]
	v_mfma_f32_16x16x32_bf16 v[20:23], v[210:213], v[194:197], v[20:23]
	v_mfma_f32_16x16x32_bf16 v[12:15], v[218:221], v[194:197], v[12:15]
	v_mfma_f32_16x16x32_bf16 v[8:11], v[210:213], v[202:205], v[8:11]
	v_mfma_f32_16x16x32_bf16 v[4:7], v[218:221], v[202:205], v[4:7]
	v_mfma_f32_16x16x32_bf16 v[52:55], v[214:217], v[166:169], v[52:55]
	v_mfma_f32_16x16x32_bf16 v[44:47], v[222:225], v[166:169], v[44:47]
	v_mfma_f32_16x16x32_bf16 v[36:39], v[214:217], v[174:177], v[36:39]
	v_mfma_f32_16x16x32_bf16 v[28:31], v[222:225], v[174:177], v[28:31]
	v_mfma_f32_16x16x32_bf16 v[20:23], v[214:217], v[198:201], v[20:23]
	v_mfma_f32_16x16x32_bf16 v[12:15], v[222:225], v[198:201], v[12:15]
	v_mfma_f32_16x16x32_bf16 v[8:11], v[214:217], v[206:209], v[8:11]
	v_mfma_f32_16x16x32_bf16 v[4:7], v[222:225], v[206:209], v[4:7]
	s_setprio 0
	s_add_i32 s45, s45, 2
	s_add_u32 s12, s12, 0x100
	s_addc_u32 s13, s13, 0
	s_add_u32 s43, s43, 0x100
	s_addc_u32 s44, s44, 0
	s_cmp_gt_u32 s45, 13
	s_barrier
	s_cbranch_scc0 .LBB0_655
	v_readlane_b32 s12, v251, 12
	v_lshl_or_b32 v144, s39, 8, v149
	v_readlane_b32 s13, v251, 13
	v_lshl_add_u32 v152, s40, 8, v146
	v_ashrrev_i32_e32 v145, 31, v144
	v_mov_b64_e32 v[142:143], s[12:13]
	s_movk_i32 s5, 0x1200
	v_mad_i64_i32 v[150:151], s[12:13], v152, s5, v[142:143]
	v_lshlrev_b64 v[144:145], 1, v[144:145]
	v_lshl_add_u64 v[150:151], v[150:151], 0, v[144:145]
	v_cvt_pk_bf16_f32 v128, v128, v129
	v_cvt_pk_bf16_f32 v129, v130, v131
	v_cvt_pk_bf16_f32 v130, v124, v125
	v_cvt_pk_bf16_f32 v131, v126, v127
	global_store_dwordx4 v[150:151], v[128:131], off sc1
	v_cvt_pk_bf16_f32 v116, v116, v117
	v_cvt_pk_bf16_f32 v117, v118, v119
	v_cvt_pk_bf16_f32 v118, v108, v109
	v_or_b32_e32 v108, 16, v152
	v_mad_i64_i32 v[108:109], s[12:13], v108, s5, v[142:143]
	v_cvt_pk_bf16_f32 v119, v110, v111
	global_store_dwordx4 v[150:151], v[116:119], off offset:256 sc1
	s_and_b64 vcc, exec, s[2:3]
	s_mov_b32 s39, s4
	v_lshl_add_u64 v[116:117], v[108:109], 0, v[144:145]
	v_cvt_pk_bf16_f32 v108, v120, v121
	v_cvt_pk_bf16_f32 v109, v122, v123
	v_cvt_pk_bf16_f32 v110, v112, v113
	v_cvt_pk_bf16_f32 v111, v114, v115
	global_store_dwordx4 v[116:117], v[108:111], off sc1
	v_cvt_pk_bf16_f32 v100, v100, v101
	v_cvt_pk_bf16_f32 v101, v102, v103
	v_cvt_pk_bf16_f32 v102, v92, v93
	v_or_b32_e32 v92, 32, v152
	v_mad_i64_i32 v[92:93], s[12:13], v92, s5, v[142:143]
	v_cvt_pk_bf16_f32 v103, v94, v95
	global_store_dwordx4 v[116:117], v[100:103], off offset:256 sc1
	s_mov_b32 s40, s6
	s_mov_b64 s[14:15], s[10:11]
	v_lshl_add_u64 v[100:101], v[92:93], 0, v[144:145]
	v_cvt_pk_bf16_f32 v92, v104, v105
	v_cvt_pk_bf16_f32 v93, v106, v107
	v_cvt_pk_bf16_f32 v94, v96, v97
	v_cvt_pk_bf16_f32 v95, v98, v99
	global_store_dwordx4 v[100:101], v[92:95], off sc1
	v_cvt_pk_bf16_f32 v84, v84, v85
	v_cvt_pk_bf16_f32 v85, v86, v87
	v_cvt_pk_bf16_f32 v86, v76, v77
	v_or_b32_e32 v76, 48, v152
	v_mad_i64_i32 v[76:77], s[12:13], v76, s5, v[142:143]
	v_cvt_pk_bf16_f32 v87, v78, v79
	global_store_dwordx4 v[100:101], v[84:87], off offset:256 sc1
	s_nop 1
	v_lshl_add_u64 v[84:85], v[76:77], 0, v[144:145]
	v_cvt_pk_bf16_f32 v76, v88, v89
	v_cvt_pk_bf16_f32 v77, v90, v91
	v_cvt_pk_bf16_f32 v78, v80, v81
	v_cvt_pk_bf16_f32 v79, v82, v83
	global_store_dwordx4 v[84:85], v[76:79], off sc1
	v_cvt_pk_bf16_f32 v72, v72, v73
	v_cvt_pk_bf16_f32 v73, v74, v75
	v_cvt_pk_bf16_f32 v74, v68, v69
	v_add_u32_e32 v68, 0x80, v152
	v_mad_i64_i32 v[68:69], s[12:13], v68, s5, v[142:143]
	v_lshl_add_u64 v[68:69], v[68:69], 0, v[144:145]
	v_cvt_pk_bf16_f32 v75, v70, v71
	global_store_dwordx4 v[84:85], v[72:75], off offset:256 sc1
	v_cvt_pk_bf16_f32 v64, v64, v65
	v_cvt_pk_bf16_f32 v65, v66, v67
	v_cvt_pk_bf16_f32 v66, v60, v61
	v_cvt_pk_bf16_f32 v67, v62, v63
	global_store_dwordx4 v[68:69], v[64:67], off sc1
	v_cvt_pk_bf16_f32 v52, v52, v53
	v_cvt_pk_bf16_f32 v53, v54, v55
	v_cvt_pk_bf16_f32 v54, v44, v45
	v_add_u32_e32 v44, 0x90, v152
	v_mad_i64_i32 v[44:45], s[12:13], v44, s5, v[142:143]
	v_cvt_pk_bf16_f32 v55, v46, v47
	global_store_dwordx4 v[68:69], v[52:55], off offset:256 sc1
	s_nop 1
	v_lshl_add_u64 v[52:53], v[44:45], 0, v[144:145]
	v_cvt_pk_bf16_f32 v44, v56, v57
	v_cvt_pk_bf16_f32 v45, v58, v59
	v_cvt_pk_bf16_f32 v46, v48, v49
	v_cvt_pk_bf16_f32 v47, v50, v51
	global_store_dwordx4 v[52:53], v[44:47], off sc1
	v_cvt_pk_bf16_f32 v36, v36, v37
	v_cvt_pk_bf16_f32 v37, v38, v39
	v_cvt_pk_bf16_f32 v38, v28, v29
	v_add_u32_e32 v28, 0xa0, v152
	v_mad_i64_i32 v[28:29], s[12:13], v28, s5, v[142:143]
	v_cvt_pk_bf16_f32 v39, v30, v31
	global_store_dwordx4 v[52:53], v[36:39], off offset:256 sc1
	s_nop 1
	v_lshl_add_u64 v[36:37], v[28:29], 0, v[144:145]
	v_cvt_pk_bf16_f32 v28, v40, v41
	v_cvt_pk_bf16_f32 v29, v42, v43
	v_cvt_pk_bf16_f32 v30, v32, v33
	v_cvt_pk_bf16_f32 v31, v34, v35
	global_store_dwordx4 v[36:37], v[28:31], off sc1
	v_cvt_pk_bf16_f32 v20, v20, v21
	v_cvt_pk_bf16_f32 v21, v22, v23
	v_cvt_pk_bf16_f32 v22, v12, v13
	v_add_u32_e32 v12, 0xb0, v152
	v_mad_i64_i32 v[12:13], s[12:13], v12, s5, v[142:143]
	v_cvt_pk_bf16_f32 v23, v14, v15
	global_store_dwordx4 v[36:37], v[20:23], off offset:256 sc1
	s_mov_b64 s[12:13], s[8:9]
	s_nop 0
	v_lshl_add_u64 v[20:21], v[12:13], 0, v[144:145]
	v_cvt_pk_bf16_f32 v12, v24, v25
	v_cvt_pk_bf16_f32 v13, v26, v27
	v_cvt_pk_bf16_f32 v14, v16, v17
	v_cvt_pk_bf16_f32 v15, v18, v19
	global_store_dwordx4 v[20:21], v[12:15], off sc1
	v_cvt_pk_bf16_f32 v8, v8, v9
	v_cvt_pk_bf16_f32 v9, v10, v11
	v_cvt_pk_bf16_f32 v10, v4, v5
	v_cvt_pk_bf16_f32 v11, v6, v7
	global_store_dwordx4 v[20:21], v[8:11], off offset:256 sc1
	s_cbranch_vccz .LBB0_652
	s_waitcnt vmcnt(0)
	s_cmpk_gt_u32 s0, 0xff
	s_cbranch_scc1 .LBB0_659
	s_barrier
